# cv42 + GEMM K-loops: in the two light (2-piece) load segments the LDS-DMA loads are issued before the ds_read fragment loads
# speedup vs baseline: 1.0107x; 1.0033x over previous
.LBB0_306:
	s_add_u32 s38, s36, 0xfff80080
	s_addc_u32 s39, s37, -1
	s_add_i32 s45, 0, 0x10000
	s_cmp_eq_u32 s27, 28
	s_cselect_b32 s43, s9, s39
	s_cselect_b32 s42, s14, s38
	v_add_u32_e32 v34, s45, v170
	s_cselect_b32 s39, s16, s26
	s_cselect_b32 s38, s17, s25
	s_add_i32 s47, 0, 0x14000
	s_add_i32 m0, s35, 0xc000
	global_load_lds_dwordx4 v152, s[36:37]
	s_add_i32 m0, s35, 0xe000
	s_nop 0
	global_load_lds_dwordx4 v156, s[36:37]
	ds_read_b128 v[160:163], v34
	ds_read_b128 v[164:167], v34 offset:1024
	ds_read_b128 v[174:177], v34 offset:2048
	ds_read_b128 v[184:187], v34 offset:3072
	v_add_u32_e32 v34, s47, v170
	ds_read_b128 v[188:191], v34
	ds_read_b128 v[192:195], v34 offset:1024
	ds_read_b128 v[196:199], v34 offset:2048
	ds_read_b128 v[200:203], v34 offset:3072
	ds_read_b128 v[214:217], v173
	ds_read_b128 v[218:221], v173 offset:1024
	ds_read_b128 v[222:225], v173 offset:2048
	ds_read_b128 v[226:229], v173 offset:3072
	ds_read_b128 v[230:233], v173 offset:4096
	ds_read_b128 v[234:237], v173 offset:5120
	ds_read_b128 v[238:241], v173 offset:6144
	ds_read_b128 v[242:245], v173 offset:7168
	s_waitcnt vmcnt(8)
	s_waitcnt lgkmcnt(0)
	s_barrier
	s_setprio 1
	s_waitcnt lgkmcnt(0)
	v_mfma_f32_16x16x32_bf16 v[132:135], v[160:163], v[214:217], v[132:135]
	v_mfma_f32_16x16x32_bf16 v[128:131], v[174:177], v[214:217], v[128:131]
	v_mfma_f32_16x16x32_bf16 v[116:119], v[160:163], v[222:225], v[116:119]
	v_mfma_f32_16x16x32_bf16 v[112:115], v[174:177], v[222:225], v[112:115]
	v_mfma_f32_16x16x32_bf16 v[100:103], v[160:163], v[230:233], v[100:103]
	v_mfma_f32_16x16x32_bf16 v[96:99], v[174:177], v[230:233], v[96:99]
	v_mfma_f32_16x16x32_bf16 v[84:87], v[160:163], v[238:241], v[84:87]
	v_mfma_f32_16x16x32_bf16 v[80:83], v[174:177], v[238:241], v[80:83]
	v_mfma_f32_16x16x32_bf16 v[132:135], v[164:167], v[218:221], v[132:135]
	v_mfma_f32_16x16x32_bf16 v[128:131], v[184:187], v[218:221], v[128:131]
	v_mfma_f32_16x16x32_bf16 v[116:119], v[164:167], v[226:229], v[116:119]
	v_mfma_f32_16x16x32_bf16 v[112:115], v[184:187], v[226:229], v[112:115]
	v_mfma_f32_16x16x32_bf16 v[100:103], v[164:167], v[234:237], v[100:103]
	v_mfma_f32_16x16x32_bf16 v[96:99], v[184:187], v[234:237], v[96:99]
	v_mfma_f32_16x16x32_bf16 v[84:87], v[164:167], v[242:245], v[84:87]
	v_mfma_f32_16x16x32_bf16 v[80:83], v[184:187], v[242:245], v[80:83]
	s_setprio 0
	s_setprio 1
	v_mfma_f32_16x16x32_bf16 v[124:127], v[188:191], v[214:217], v[124:127]
	v_mfma_f32_16x16x32_bf16 v[120:123], v[196:199], v[214:217], v[120:123]
	v_mfma_f32_16x16x32_bf16 v[108:111], v[188:191], v[222:225], v[108:111]
	v_mfma_f32_16x16x32_bf16 v[104:107], v[196:199], v[222:225], v[104:107]
	v_mfma_f32_16x16x32_bf16 v[92:95], v[188:191], v[230:233], v[92:95]
	v_mfma_f32_16x16x32_bf16 v[88:91], v[196:199], v[230:233], v[88:91]
	v_mfma_f32_16x16x32_bf16 v[76:79], v[188:191], v[238:241], v[76:79]
	v_mfma_f32_16x16x32_bf16 v[72:75], v[196:199], v[238:241], v[72:75]
	v_mfma_f32_16x16x32_bf16 v[124:127], v[192:195], v[218:221], v[124:127]
	v_mfma_f32_16x16x32_bf16 v[120:123], v[200:203], v[218:221], v[120:123]
	v_mfma_f32_16x16x32_bf16 v[108:111], v[192:195], v[226:229], v[108:111]
	v_mfma_f32_16x16x32_bf16 v[104:107], v[200:203], v[226:229], v[104:107]
	v_mfma_f32_16x16x32_bf16 v[92:95], v[192:195], v[234:237], v[92:95]
	v_mfma_f32_16x16x32_bf16 v[88:91], v[200:203], v[234:237], v[88:91]
	v_mfma_f32_16x16x32_bf16 v[76:79], v[192:195], v[242:245], v[76:79]
	v_mfma_f32_16x16x32_bf16 v[72:75], v[200:203], v[242:245], v[72:75]
	s_setprio 0
	s_barrier
	s_add_u32 s98, s38, s22
	s_addc_u32 s99, s39, s23
	s_add_u32 s100, s42, s22
	s_addc_u32 s101, s43, s23
	s_add_i32 s45, s45, s53
	s_mov_b32 m0, s45
	ds_read_b128 v[214:217], v173 offset:16384
	ds_read_b128 v[218:221], v173 offset:17408
	ds_read_b128 v[222:225], v173 offset:18432
	ds_read_b128 v[226:229], v173 offset:19456
	ds_read_b128 v[230:233], v173 offset:20480
	ds_read_b128 v[234:237], v173 offset:21504
	ds_read_b128 v[238:241], v173 offset:22528
	ds_read_b128 v[242:245], v173 offset:23552
	global_load_lds_dwordx4 v136, s[38:39]
	s_add_i32 m0, s45, 0x2000
	s_add_u32 s70, s38, 0x80000
	s_addc_u32 s71, s39, 0
	s_add_i32 s45, s47, s53
	global_load_lds_dwordx4 v140, s[38:39]
	s_mov_b32 m0, s45
	global_load_lds_dwordx4 v136, s[70:71]
	s_add_i32 m0, s45, 0x2000
	s_nop 0
	global_load_lds_dwordx4 v140, s[70:71]
	s_mov_b32 m0, s35
	s_nop 0
	global_load_lds_dwordx4 v14, s[42:43]
	s_mov_b32 m0, s54
	s_nop 0
	global_load_lds_dwordx4 v138, s[42:43]
	s_waitcnt vmcnt(8)
	s_waitcnt lgkmcnt(0)
	s_barrier
	s_setprio 1
	s_waitcnt lgkmcnt(0)
	v_mfma_f32_16x16x32_bf16 v[68:71], v[160:163], v[214:217], v[68:71]
	v_mfma_f32_16x16x32_bf16 v[64:67], v[174:177], v[214:217], v[64:67]
	v_mfma_f32_16x16x32_bf16 v[52:55], v[160:163], v[222:225], v[52:55]
	v_mfma_f32_16x16x32_bf16 v[48:51], v[174:177], v[222:225], v[48:51]
	v_mfma_f32_16x16x32_bf16 v[36:39], v[160:163], v[230:233], v[36:39]
	v_mfma_f32_16x16x32_bf16 v[30:33], v[174:177], v[230:233], v[30:33]
	v_mfma_f32_16x16x32_bf16 v[18:21], v[160:163], v[238:241], v[18:21]
	v_mfma_f32_16x16x32_bf16 v[10:13], v[174:177], v[238:241], v[10:13]
	v_mfma_f32_16x16x32_bf16 v[68:71], v[164:167], v[218:221], v[68:71]
	v_mfma_f32_16x16x32_bf16 v[64:67], v[184:187], v[218:221], v[64:67]
	v_mfma_f32_16x16x32_bf16 v[52:55], v[164:167], v[226:229], v[52:55]
	v_mfma_f32_16x16x32_bf16 v[48:51], v[184:187], v[226:229], v[48:51]
	v_mfma_f32_16x16x32_bf16 v[36:39], v[164:167], v[234:237], v[36:39]
	v_mfma_f32_16x16x32_bf16 v[30:33], v[184:187], v[234:237], v[30:33]
	v_mfma_f32_16x16x32_bf16 v[18:21], v[164:167], v[242:245], v[18:21]
	v_mfma_f32_16x16x32_bf16 v[10:13], v[184:187], v[242:245], v[10:13]
	s_setprio 0
	s_setprio 1
	v_mfma_f32_16x16x32_bf16 v[60:63], v[188:191], v[214:217], v[60:63]
	v_mfma_f32_16x16x32_bf16 v[56:59], v[196:199], v[214:217], v[56:59]
	v_mfma_f32_16x16x32_bf16 v[44:47], v[188:191], v[222:225], v[44:47]
	v_mfma_f32_16x16x32_bf16 v[40:43], v[196:199], v[222:225], v[40:43]
	v_mfma_f32_16x16x32_bf16 v[26:29], v[188:191], v[230:233], v[26:29]
	v_mfma_f32_16x16x32_bf16 v[22:25], v[196:199], v[230:233], v[22:25]
	v_mfma_f32_16x16x32_bf16 v[6:9], v[188:191], v[238:241], v[6:9]
	v_mfma_f32_16x16x32_bf16 v[2:5], v[196:199], v[238:241], v[2:5]
	v_mfma_f32_16x16x32_bf16 v[60:63], v[192:195], v[218:221], v[60:63]
	v_mfma_f32_16x16x32_bf16 v[56:59], v[200:203], v[218:221], v[56:59]
	v_mfma_f32_16x16x32_bf16 v[44:47], v[192:195], v[226:229], v[44:47]
	v_mfma_f32_16x16x32_bf16 v[40:43], v[200:203], v[226:229], v[40:43]
	v_mfma_f32_16x16x32_bf16 v[26:29], v[192:195], v[234:237], v[26:29]
	v_mfma_f32_16x16x32_bf16 v[22:25], v[200:203], v[234:237], v[22:25]
	v_mfma_f32_16x16x32_bf16 v[6:9], v[192:195], v[242:245], v[6:9]
	v_mfma_f32_16x16x32_bf16 v[2:5], v[200:203], v[242:245], v[2:5]
	s_setprio 0
	s_barrier
	s_add_i32 s45, 0, 0x18000
	v_add_u32_e32 v34, s45, v170
	s_add_i32 s47, 0, 0x1c000
	s_add_u32 s42, s42, 0x80000
	s_addc_u32 s43, s43, 0
	s_mov_b32 m0, s55
	global_load_lds_dwordx4 v14, s[42:43]
	s_mov_b32 m0, s60
	s_nop 0
	global_load_lds_dwordx4 v138, s[42:43]
	ds_read_b128 v[160:163], v34
	ds_read_b128 v[164:167], v34 offset:1024
	ds_read_b128 v[174:177], v34 offset:2048
	ds_read_b128 v[184:187], v34 offset:3072
	v_add_u32_e32 v34, s47, v170
	ds_read_b128 v[188:191], v34
	ds_read_b128 v[192:195], v34 offset:1024
	ds_read_b128 v[196:199], v34 offset:2048
	ds_read_b128 v[200:203], v34 offset:3072
	ds_read_b128 v[214:217], v173 offset:32768
	ds_read_b128 v[218:221], v173 offset:33792
	ds_read_b128 v[222:225], v173 offset:34816
	ds_read_b128 v[226:229], v173 offset:35840
	ds_read_b128 v[230:233], v173 offset:36864
	ds_read_b128 v[234:237], v173 offset:37888
	ds_read_b128 v[238:241], v173 offset:38912
	ds_read_b128 v[242:245], v173 offset:39936
	s_waitcnt vmcnt(8)
	s_waitcnt lgkmcnt(0)
	s_barrier
	s_setprio 1
	s_waitcnt lgkmcnt(0)
	v_mfma_f32_16x16x32_bf16 v[132:135], v[160:163], v[214:217], v[132:135]
	v_mfma_f32_16x16x32_bf16 v[128:131], v[174:177], v[214:217], v[128:131]
	v_mfma_f32_16x16x32_bf16 v[116:119], v[160:163], v[222:225], v[116:119]
	v_mfma_f32_16x16x32_bf16 v[112:115], v[174:177], v[222:225], v[112:115]
	v_mfma_f32_16x16x32_bf16 v[100:103], v[160:163], v[230:233], v[100:103]
	v_mfma_f32_16x16x32_bf16 v[96:99], v[174:177], v[230:233], v[96:99]
	v_mfma_f32_16x16x32_bf16 v[84:87], v[160:163], v[238:241], v[84:87]
	v_mfma_f32_16x16x32_bf16 v[80:83], v[174:177], v[238:241], v[80:83]
	v_mfma_f32_16x16x32_bf16 v[132:135], v[164:167], v[218:221], v[132:135]
	v_mfma_f32_16x16x32_bf16 v[128:131], v[184:187], v[218:221], v[128:131]
	v_mfma_f32_16x16x32_bf16 v[116:119], v[164:167], v[226:229], v[116:119]
	v_mfma_f32_16x16x32_bf16 v[112:115], v[184:187], v[226:229], v[112:115]
	v_mfma_f32_16x16x32_bf16 v[100:103], v[164:167], v[234:237], v[100:103]
	v_mfma_f32_16x16x32_bf16 v[96:99], v[184:187], v[234:237], v[96:99]
	v_mfma_f32_16x16x32_bf16 v[84:87], v[164:167], v[242:245], v[84:87]
	v_mfma_f32_16x16x32_bf16 v[80:83], v[184:187], v[242:245], v[80:83]
	s_setprio 0
	s_setprio 1
	v_mfma_f32_16x16x32_bf16 v[124:127], v[188:191], v[214:217], v[124:127]
	v_mfma_f32_16x16x32_bf16 v[120:123], v[196:199], v[214:217], v[120:123]
	v_mfma_f32_16x16x32_bf16 v[108:111], v[188:191], v[222:225], v[108:111]
	v_mfma_f32_16x16x32_bf16 v[104:107], v[196:199], v[222:225], v[104:107]
	v_mfma_f32_16x16x32_bf16 v[92:95], v[188:191], v[230:233], v[92:95]
	v_mfma_f32_16x16x32_bf16 v[88:91], v[196:199], v[230:233], v[88:91]
	v_mfma_f32_16x16x32_bf16 v[76:79], v[188:191], v[238:241], v[76:79]
	v_mfma_f32_16x16x32_bf16 v[72:75], v[196:199], v[238:241], v[72:75]
	v_mfma_f32_16x16x32_bf16 v[124:127], v[192:195], v[218:221], v[124:127]
	v_mfma_f32_16x16x32_bf16 v[120:123], v[200:203], v[218:221], v[120:123]
	v_mfma_f32_16x16x32_bf16 v[108:111], v[192:195], v[226:229], v[108:111]
	v_mfma_f32_16x16x32_bf16 v[104:107], v[200:203], v[226:229], v[104:107]
	v_mfma_f32_16x16x32_bf16 v[92:95], v[192:195], v[234:237], v[92:95]
	v_mfma_f32_16x16x32_bf16 v[88:91], v[200:203], v[234:237], v[88:91]
	v_mfma_f32_16x16x32_bf16 v[76:79], v[192:195], v[242:245], v[76:79]
	v_mfma_f32_16x16x32_bf16 v[72:75], v[200:203], v[242:245], v[72:75]
	s_setprio 0
	s_barrier
	s_add_i32 s42, s45, s53
	s_mov_b32 m0, s42
	ds_read_b128 v[214:217], v173 offset:49152
	ds_read_b128 v[218:221], v173 offset:50176
	ds_read_b128 v[222:225], v173 offset:51200
	ds_read_b128 v[226:229], v173 offset:52224
	ds_read_b128 v[230:233], v173 offset:53248
	ds_read_b128 v[234:237], v173 offset:54272
	ds_read_b128 v[238:241], v173 offset:55296
	ds_read_b128 v[242:245], v173 offset:56320
	global_load_lds_dwordx4 v136, s[98:99]
	s_add_i32 m0, s42, 0x2000
	s_add_u32 s38, s38, 0x80080
	s_addc_u32 s39, s39, 0
	s_add_i32 s42, s47, s53
	global_load_lds_dwordx4 v140, s[98:99]
	s_mov_b32 m0, s42
	s_nop 0
	global_load_lds_dwordx4 v136, s[38:39]
	s_add_i32 m0, s42, 0x2000
	s_nop 0
	global_load_lds_dwordx4 v140, s[38:39]
	s_mov_b32 m0, s61
	s_nop 0
	global_load_lds_dwordx4 v14, s[100:101]
	s_mov_b32 m0, s64
	s_nop 0
	global_load_lds_dwordx4 v138, s[100:101]
	s_waitcnt vmcnt(8)
	s_waitcnt lgkmcnt(0)
	s_barrier
	s_setprio 1
	s_waitcnt lgkmcnt(0)
	v_mfma_f32_16x16x32_bf16 v[68:71], v[160:163], v[214:217], v[68:71]
	v_mfma_f32_16x16x32_bf16 v[64:67], v[174:177], v[214:217], v[64:67]
	v_mfma_f32_16x16x32_bf16 v[52:55], v[160:163], v[222:225], v[52:55]
	v_mfma_f32_16x16x32_bf16 v[48:51], v[174:177], v[222:225], v[48:51]
	v_mfma_f32_16x16x32_bf16 v[36:39], v[160:163], v[230:233], v[36:39]
	v_mfma_f32_16x16x32_bf16 v[30:33], v[174:177], v[230:233], v[30:33]
	v_mfma_f32_16x16x32_bf16 v[18:21], v[160:163], v[238:241], v[18:21]
	v_mfma_f32_16x16x32_bf16 v[10:13], v[174:177], v[238:241], v[10:13]
	v_mfma_f32_16x16x32_bf16 v[68:71], v[164:167], v[218:221], v[68:71]
	v_mfma_f32_16x16x32_bf16 v[64:67], v[184:187], v[218:221], v[64:67]
	v_mfma_f32_16x16x32_bf16 v[52:55], v[164:167], v[226:229], v[52:55]
	v_mfma_f32_16x16x32_bf16 v[48:51], v[184:187], v[226:229], v[48:51]
	v_mfma_f32_16x16x32_bf16 v[36:39], v[164:167], v[234:237], v[36:39]
	v_mfma_f32_16x16x32_bf16 v[30:33], v[184:187], v[234:237], v[30:33]
	v_mfma_f32_16x16x32_bf16 v[18:21], v[164:167], v[242:245], v[18:21]
	v_mfma_f32_16x16x32_bf16 v[10:13], v[184:187], v[242:245], v[10:13]
	s_setprio 0
	s_setprio 1
	v_mfma_f32_16x16x32_bf16 v[60:63], v[188:191], v[214:217], v[60:63]
	v_mfma_f32_16x16x32_bf16 v[56:59], v[196:199], v[214:217], v[56:59]
	v_mfma_f32_16x16x32_bf16 v[44:47], v[188:191], v[222:225], v[44:47]
	v_mfma_f32_16x16x32_bf16 v[40:43], v[196:199], v[222:225], v[40:43]
	v_mfma_f32_16x16x32_bf16 v[26:29], v[188:191], v[230:233], v[26:29]
	v_mfma_f32_16x16x32_bf16 v[22:25], v[196:199], v[230:233], v[22:25]
	v_mfma_f32_16x16x32_bf16 v[6:9], v[188:191], v[238:241], v[6:9]
	v_mfma_f32_16x16x32_bf16 v[2:5], v[196:199], v[238:241], v[2:5]
	v_mfma_f32_16x16x32_bf16 v[60:63], v[192:195], v[218:221], v[60:63]
	v_mfma_f32_16x16x32_bf16 v[56:59], v[200:203], v[218:221], v[56:59]
	v_mfma_f32_16x16x32_bf16 v[44:47], v[192:195], v[226:229], v[44:47]
	v_mfma_f32_16x16x32_bf16 v[40:43], v[200:203], v[226:229], v[40:43]
	v_mfma_f32_16x16x32_bf16 v[26:29], v[192:195], v[234:237], v[26:29]
	v_mfma_f32_16x16x32_bf16 v[22:25], v[200:203], v[234:237], v[22:25]
	v_mfma_f32_16x16x32_bf16 v[6:9], v[192:195], v[242:245], v[6:9]
	v_mfma_f32_16x16x32_bf16 v[2:5], v[200:203], v[242:245], v[2:5]
	s_setprio 0
	s_barrier
	s_add_i32 s27, s27, 2
	s_add_u32 s36, s36, 0x100
	s_addc_u32 s37, s37, 0
	s_add_u32 s25, s25, 0x100
	s_addc_u32 s26, s26, 0
	s_cmp_gt_u32 s27, 29
	s_cbranch_scc0 .LBB0_306
	s_and_b64 vcc, exec, s[28:29]
	s_cbranch_vccz .LBB0_309
	s_barrier

.LBB0_1124:
	s_add_i32 vcc_lo, s44, 2
	s_add_u32 s38, s8, 0x100
	s_addc_u32 s39, s9, 0
	s_add_i32 s72, 0, 0x10000
	s_cmp_eq_u32 s29, s44
	s_cselect_b32 s47, s35, s39
	s_cselect_b32 s46, s34, s38
	v_add_u32_e32 v34, s72, v183
	s_cselect_b32 s45, s49, s71
	s_cselect_b32 s44, s48, s70
	s_add_i32 s73, 0, 0x14000
	s_add_i32 m0, s25, 0xc000
	global_load_lds_dwordx4 v192, s[8:9]
	s_add_i32 m0, s25, 0xe000
	s_nop 0
	global_load_lds_dwordx4 v194, s[8:9]
	ds_read_b128 v[42:45], v34
	ds_read_b128 v[46:49], v34 offset:1024
	ds_read_b128 v[74:77], v34 offset:2048
	ds_read_b128 v[78:81], v34 offset:3072
	v_add_u32_e32 v34, s73, v183
	ds_read_b128 v[106:109], v34
	ds_read_b128 v[110:113], v34 offset:1024
	ds_read_b128 v[138:141], v34 offset:2048
	ds_read_b128 v[142:145], v34 offset:3072
	ds_read_b128 v[170:173], v205
	ds_read_b128 v[174:177], v205 offset:1024
	ds_read_b128 v[196:199], v205 offset:2048
	ds_read_b128 v[200:203], v205 offset:3072
	ds_read_b128 v[214:217], v205 offset:4096
	ds_read_b128 v[218:221], v205 offset:5120
	ds_read_b128 v[222:225], v205 offset:6144
	ds_read_b128 v[226:229], v205 offset:7168
	s_waitcnt vmcnt(8)
	s_waitcnt lgkmcnt(0)
	s_barrier
	s_setprio 1
	s_waitcnt lgkmcnt(0)
	v_mfma_f32_16x16x32_bf16 v[62:65], v[42:45], v[170:173], v[62:65]
	v_mfma_f32_16x16x32_bf16 v[58:61], v[74:77], v[170:173], v[58:61]
	v_mfma_f32_16x16x32_bf16 v[94:97], v[42:45], v[196:199], v[94:97]
	v_mfma_f32_16x16x32_bf16 v[90:93], v[74:77], v[196:199], v[90:93]
	v_mfma_f32_16x16x32_bf16 v[118:121], v[42:45], v[214:217], v[118:121]
	v_mfma_f32_16x16x32_bf16 v[114:117], v[74:77], v[214:217], v[114:117]
	v_mfma_f32_16x16x32_bf16 v[134:137], v[42:45], v[222:225], v[134:137]
	v_mfma_f32_16x16x32_bf16 v[130:133], v[74:77], v[222:225], v[130:133]
	v_mfma_f32_16x16x32_bf16 v[62:65], v[46:49], v[174:177], v[62:65]
	v_mfma_f32_16x16x32_bf16 v[58:61], v[78:81], v[174:177], v[58:61]
	v_mfma_f32_16x16x32_bf16 v[94:97], v[46:49], v[200:203], v[94:97]
	v_mfma_f32_16x16x32_bf16 v[90:93], v[78:81], v[200:203], v[90:93]
	v_mfma_f32_16x16x32_bf16 v[118:121], v[46:49], v[218:221], v[118:121]
	v_mfma_f32_16x16x32_bf16 v[114:117], v[78:81], v[218:221], v[114:117]
	v_mfma_f32_16x16x32_bf16 v[134:137], v[46:49], v[226:229], v[134:137]
	v_mfma_f32_16x16x32_bf16 v[130:133], v[78:81], v[226:229], v[130:133]
	s_setprio 0
	s_setprio 1
	v_mfma_f32_16x16x32_bf16 v[166:169], v[106:109], v[170:173], v[166:169]
	v_mfma_f32_16x16x32_bf16 v[162:165], v[138:141], v[170:173], v[162:165]
	v_mfma_f32_16x16x32_bf16 v[158:161], v[106:109], v[196:199], v[158:161]
	v_mfma_f32_16x16x32_bf16 v[154:157], v[138:141], v[196:199], v[154:157]
	v_mfma_f32_16x16x32_bf16 v[150:153], v[106:109], v[214:217], v[150:153]
	v_mfma_f32_16x16x32_bf16 v[146:149], v[138:141], v[214:217], v[146:149]
	v_mfma_f32_16x16x32_bf16 v[126:129], v[106:109], v[222:225], v[126:129]
	v_mfma_f32_16x16x32_bf16 v[122:125], v[138:141], v[222:225], v[122:125]
	v_mfma_f32_16x16x32_bf16 v[166:169], v[110:113], v[174:177], v[166:169]
	v_mfma_f32_16x16x32_bf16 v[162:165], v[142:145], v[174:177], v[162:165]
	v_mfma_f32_16x16x32_bf16 v[158:161], v[110:113], v[200:203], v[158:161]
	v_mfma_f32_16x16x32_bf16 v[154:157], v[142:145], v[200:203], v[154:157]
	v_mfma_f32_16x16x32_bf16 v[150:153], v[110:113], v[218:221], v[150:153]
	v_mfma_f32_16x16x32_bf16 v[146:149], v[142:145], v[218:221], v[146:149]
	v_mfma_f32_16x16x32_bf16 v[126:129], v[110:113], v[226:229], v[126:129]
	v_mfma_f32_16x16x32_bf16 v[122:125], v[142:145], v[226:229], v[122:125]
	s_setprio 0
	s_barrier
	s_add_u32 s98, s44, s22
	s_addc_u32 s99, s45, s23
	s_add_u32 s100, s46, s22
	s_addc_u32 s101, s47, s23
	s_add_i32 s8, s72, s20
	s_mov_b32 m0, s8
	ds_read_b128 v[170:173], v205 offset:16384
	ds_read_b128 v[174:177], v205 offset:17408
	ds_read_b128 v[196:199], v205 offset:18432
	ds_read_b128 v[200:203], v205 offset:19456
	ds_read_b128 v[214:217], v205 offset:20480
	ds_read_b128 v[218:221], v205 offset:21504
	ds_read_b128 v[222:225], v205 offset:22528
	ds_read_b128 v[226:229], v205 offset:23552
	global_load_lds_dwordx4 v184, s[44:45]
	s_add_i32 m0, s8, 0x2000
	s_add_u32 s8, s44, 0xc0000
	s_addc_u32 s9, s45, 0
	s_add_i32 s72, s73, s20
	global_load_lds_dwordx4 v188, s[44:45]
	s_mov_b32 m0, s72
	global_load_lds_dwordx4 v184, s[8:9]
	s_add_i32 m0, s72, 0x2000
	global_load_lds_dwordx4 v188, s[8:9]
	s_mov_b32 m0, s25
	s_nop 0
	global_load_lds_dwordx4 v14, s[46:47]
	s_mov_b32 m0, s26
	s_nop 0
	global_load_lds_dwordx4 v186, s[46:47]
	s_waitcnt vmcnt(8)
	s_waitcnt lgkmcnt(0)
	s_barrier
	s_setprio 1
	s_waitcnt lgkmcnt(0)
	v_mfma_f32_16x16x32_bf16 v[102:105], v[42:45], v[170:173], v[102:105]
	v_mfma_f32_16x16x32_bf16 v[98:101], v[74:77], v[170:173], v[98:101]
	v_mfma_f32_16x16x32_bf16 v[70:73], v[42:45], v[196:199], v[70:73]
	v_mfma_f32_16x16x32_bf16 v[66:69], v[74:77], v[196:199], v[66:69]
	v_mfma_f32_16x16x32_bf16 v[36:39], v[42:45], v[214:217], v[38:41]
	v_mfma_f32_16x16x32_bf16 v[30:33], v[74:77], v[214:217], v[30:33]
	v_mfma_f32_16x16x32_bf16 v[18:21], v[42:45], v[222:225], v[18:21]
	v_mfma_f32_16x16x32_bf16 v[10:13], v[74:77], v[222:225], v[10:13]
	v_mfma_f32_16x16x32_bf16 v[102:105], v[46:49], v[174:177], v[102:105]
	v_mfma_f32_16x16x32_bf16 v[98:101], v[78:81], v[174:177], v[98:101]
	v_mfma_f32_16x16x32_bf16 v[70:73], v[46:49], v[200:203], v[70:73]
	v_mfma_f32_16x16x32_bf16 v[66:69], v[78:81], v[200:203], v[66:69]
	v_mfma_f32_16x16x32_bf16 v[36:39], v[46:49], v[218:221], v[36:39]
	v_mfma_f32_16x16x32_bf16 v[30:33], v[78:81], v[218:221], v[30:33]
	v_mfma_f32_16x16x32_bf16 v[18:21], v[46:49], v[226:229], v[18:21]
	v_mfma_f32_16x16x32_bf16 v[10:13], v[78:81], v[226:229], v[10:13]
	s_setprio 0
	s_setprio 1
	v_mfma_f32_16x16x32_bf16 v[54:57], v[106:109], v[196:199], v[54:57]
	v_mfma_f32_16x16x32_bf16 v[50:53], v[138:141], v[196:199], v[50:53]
	v_mfma_f32_16x16x32_bf16 v[26:29], v[106:109], v[214:217], v[26:29]
	v_mfma_f32_16x16x32_bf16 v[22:25], v[138:141], v[214:217], v[22:25]
	v_mfma_f32_16x16x32_bf16 v[6:9], v[106:109], v[222:225], v[6:9]
	v_mfma_f32_16x16x32_bf16 v[2:5], v[138:141], v[222:225], v[2:5]
	v_mfma_f32_16x16x32_bf16 v[40:43], v[106:109], v[170:173], v[86:89]
	v_mfma_f32_16x16x32_bf16 v[46:49], v[138:141], v[170:173], v[82:85]
	v_mfma_f32_16x16x32_bf16 v[54:57], v[110:113], v[200:203], v[54:57]
	v_mfma_f32_16x16x32_bf16 v[50:53], v[142:145], v[200:203], v[50:53]
	v_mfma_f32_16x16x32_bf16 v[26:29], v[110:113], v[218:221], v[26:29]
	v_mfma_f32_16x16x32_bf16 v[22:25], v[142:145], v[218:221], v[22:25]
	v_mfma_f32_16x16x32_bf16 v[6:9], v[110:113], v[226:229], v[6:9]
	v_mfma_f32_16x16x32_bf16 v[2:5], v[142:145], v[226:229], v[2:5]
	v_mfma_f32_16x16x32_bf16 v[42:45], v[110:113], v[174:177], v[40:43]
	v_mfma_f32_16x16x32_bf16 v[46:49], v[142:145], v[174:177], v[46:49]
	s_setprio 0
	s_barrier
	s_add_i32 s72, 0, 0x18000
	v_add_u32_e32 v34, s72, v183
	s_add_i32 s73, 0, 0x1c000
	s_add_u32 s8, s46, 0xc0000
	s_addc_u32 s9, s47, 0
	s_mov_b32 m0, s27
	global_load_lds_dwordx4 v14, s[8:9]
	s_mov_b32 m0, s31
	s_nop 0
	global_load_lds_dwordx4 v186, s[8:9]
	ds_read_b128 v[74:77], v34
	ds_read_b128 v[78:81], v34 offset:1024
	ds_read_b128 v[82:85], v34 offset:2048
	ds_read_b128 v[86:89], v34 offset:3072
	v_add_u32_e32 v34, s73, v183
	ds_read_b128 v[106:109], v34
	ds_read_b128 v[110:113], v34 offset:1024
	ds_read_b128 v[138:141], v34 offset:2048
	ds_read_b128 v[142:145], v34 offset:3072
	ds_read_b128 v[170:173], v205 offset:32768
	ds_read_b128 v[174:177], v205 offset:33792
	ds_read_b128 v[196:199], v205 offset:34816
	ds_read_b128 v[200:203], v205 offset:35840
	ds_read_b128 v[214:217], v205 offset:36864
	ds_read_b128 v[218:221], v205 offset:37888
	ds_read_b128 v[222:225], v205 offset:38912
	ds_read_b128 v[226:229], v205 offset:39936
	s_waitcnt vmcnt(8)
	s_waitcnt lgkmcnt(0)
	s_barrier
	s_setprio 1
	s_waitcnt lgkmcnt(0)
	v_mfma_f32_16x16x32_bf16 v[62:65], v[74:77], v[170:173], v[62:65]
	v_mfma_f32_16x16x32_bf16 v[58:61], v[82:85], v[170:173], v[58:61]
	v_mfma_f32_16x16x32_bf16 v[94:97], v[74:77], v[196:199], v[94:97]
	v_mfma_f32_16x16x32_bf16 v[90:93], v[82:85], v[196:199], v[90:93]
	v_mfma_f32_16x16x32_bf16 v[118:121], v[74:77], v[214:217], v[118:121]
	v_mfma_f32_16x16x32_bf16 v[114:117], v[82:85], v[214:217], v[114:117]
	v_mfma_f32_16x16x32_bf16 v[134:137], v[74:77], v[222:225], v[134:137]
	v_mfma_f32_16x16x32_bf16 v[130:133], v[82:85], v[222:225], v[130:133]
	v_mfma_f32_16x16x32_bf16 v[62:65], v[78:81], v[174:177], v[62:65]
	v_mfma_f32_16x16x32_bf16 v[58:61], v[86:89], v[174:177], v[58:61]
	v_mfma_f32_16x16x32_bf16 v[94:97], v[78:81], v[200:203], v[94:97]
	v_mfma_f32_16x16x32_bf16 v[90:93], v[86:89], v[200:203], v[90:93]
	v_mfma_f32_16x16x32_bf16 v[118:121], v[78:81], v[218:221], v[118:121]
	v_mfma_f32_16x16x32_bf16 v[114:117], v[86:89], v[218:221], v[114:117]
	v_mfma_f32_16x16x32_bf16 v[134:137], v[78:81], v[226:229], v[134:137]
	v_mfma_f32_16x16x32_bf16 v[130:133], v[86:89], v[226:229], v[130:133]
	s_setprio 0
	s_setprio 1
	v_mfma_f32_16x16x32_bf16 v[166:169], v[106:109], v[170:173], v[166:169]
	v_mfma_f32_16x16x32_bf16 v[162:165], v[138:141], v[170:173], v[162:165]
	v_mfma_f32_16x16x32_bf16 v[158:161], v[106:109], v[196:199], v[158:161]
	v_mfma_f32_16x16x32_bf16 v[154:157], v[138:141], v[196:199], v[154:157]
	v_mfma_f32_16x16x32_bf16 v[150:153], v[106:109], v[214:217], v[150:153]
	v_mfma_f32_16x16x32_bf16 v[146:149], v[138:141], v[214:217], v[146:149]
	v_mfma_f32_16x16x32_bf16 v[126:129], v[106:109], v[222:225], v[126:129]
	v_mfma_f32_16x16x32_bf16 v[122:125], v[138:141], v[222:225], v[122:125]
	v_mfma_f32_16x16x32_bf16 v[166:169], v[110:113], v[174:177], v[166:169]
	v_mfma_f32_16x16x32_bf16 v[162:165], v[142:145], v[174:177], v[162:165]
	v_mfma_f32_16x16x32_bf16 v[158:161], v[110:113], v[200:203], v[158:161]
	v_mfma_f32_16x16x32_bf16 v[154:157], v[142:145], v[200:203], v[154:157]
	v_mfma_f32_16x16x32_bf16 v[150:153], v[110:113], v[218:221], v[150:153]
	v_mfma_f32_16x16x32_bf16 v[146:149], v[142:145], v[218:221], v[146:149]
	v_mfma_f32_16x16x32_bf16 v[126:129], v[110:113], v[226:229], v[126:129]
	v_mfma_f32_16x16x32_bf16 v[122:125], v[142:145], v[226:229], v[122:125]
	s_setprio 0
	s_barrier
	s_add_i32 s8, s72, s20
	s_mov_b32 m0, s8
	ds_read_b128 v[170:173], v205 offset:49152
	ds_read_b128 v[174:177], v205 offset:50176
	ds_read_b128 v[196:199], v205 offset:51200
	ds_read_b128 v[200:203], v205 offset:52224
	ds_read_b128 v[214:217], v205 offset:53248
	ds_read_b128 v[218:221], v205 offset:54272
	ds_read_b128 v[222:225], v205 offset:55296
	ds_read_b128 v[226:229], v205 offset:56320
	global_load_lds_dwordx4 v184, s[98:99]
	s_add_i32 m0, s8, 0x2000
	s_add_u32 s8, s44, 0xc0080
	s_addc_u32 s9, s45, 0
	s_add_i32 s44, s73, s20
	global_load_lds_dwordx4 v188, s[98:99]
	s_mov_b32 m0, s44
	s_nop 0
	global_load_lds_dwordx4 v184, s[8:9]
	s_add_i32 m0, s44, 0x2000
	s_nop 0
	global_load_lds_dwordx4 v188, s[8:9]
	s_mov_b32 m0, s52
	s_nop 0
	global_load_lds_dwordx4 v14, s[100:101]
	s_mov_b32 m0, s53
	s_nop 0
	global_load_lds_dwordx4 v186, s[100:101]
	s_waitcnt vmcnt(8)
	s_waitcnt lgkmcnt(0)
	s_barrier
	s_setprio 1
	s_waitcnt lgkmcnt(0)
	v_mfma_f32_16x16x32_bf16 v[102:105], v[74:77], v[170:173], v[102:105]
	v_mfma_f32_16x16x32_bf16 v[98:101], v[82:85], v[170:173], v[98:101]
	v_mfma_f32_16x16x32_bf16 v[70:73], v[74:77], v[196:199], v[70:73]
	v_mfma_f32_16x16x32_bf16 v[66:69], v[82:85], v[196:199], v[66:69]
	v_mfma_f32_16x16x32_bf16 v[36:39], v[74:77], v[214:217], v[36:39]
	v_mfma_f32_16x16x32_bf16 v[30:33], v[82:85], v[214:217], v[30:33]
	v_mfma_f32_16x16x32_bf16 v[18:21], v[74:77], v[222:225], v[18:21]
	v_mfma_f32_16x16x32_bf16 v[10:13], v[82:85], v[222:225], v[10:13]
	v_mfma_f32_16x16x32_bf16 v[102:105], v[78:81], v[174:177], v[102:105]
	v_mfma_f32_16x16x32_bf16 v[98:101], v[86:89], v[174:177], v[98:101]
	v_mfma_f32_16x16x32_bf16 v[70:73], v[78:81], v[200:203], v[70:73]
	v_mfma_f32_16x16x32_bf16 v[66:69], v[86:89], v[200:203], v[66:69]
	v_mfma_f32_16x16x32_bf16 v[38:41], v[78:81], v[218:221], v[36:39]
	v_mfma_f32_16x16x32_bf16 v[30:33], v[86:89], v[218:221], v[30:33]
	v_mfma_f32_16x16x32_bf16 v[18:21], v[78:81], v[226:229], v[18:21]
	v_mfma_f32_16x16x32_bf16 v[10:13], v[86:89], v[226:229], v[10:13]
	s_setprio 0
	s_setprio 1
	v_mfma_f32_16x16x32_bf16 v[42:45], v[106:109], v[170:173], v[42:45]
	v_mfma_f32_16x16x32_bf16 v[86:89], v[110:113], v[174:177], v[42:45]
	v_mfma_f32_16x16x32_bf16 v[42:45], v[138:141], v[170:173], v[46:49]
	v_mfma_f32_16x16x32_bf16 v[82:85], v[142:145], v[174:177], v[42:45]
	v_mfma_f32_16x16x32_bf16 v[42:45], v[106:109], v[196:199], v[54:57]
	v_mfma_f32_16x16x32_bf16 v[54:57], v[110:113], v[200:203], v[42:45]
	v_mfma_f32_16x16x32_bf16 v[42:45], v[138:141], v[196:199], v[50:53]
	v_mfma_f32_16x16x32_bf16 v[26:29], v[106:109], v[214:217], v[26:29]
	v_mfma_f32_16x16x32_bf16 v[22:25], v[138:141], v[214:217], v[22:25]
	v_mfma_f32_16x16x32_bf16 v[6:9], v[106:109], v[222:225], v[6:9]
	v_mfma_f32_16x16x32_bf16 v[2:5], v[138:141], v[222:225], v[2:5]
	v_mfma_f32_16x16x32_bf16 v[50:53], v[142:145], v[200:203], v[42:45]
	v_mfma_f32_16x16x32_bf16 v[26:29], v[110:113], v[218:221], v[26:29]
	v_mfma_f32_16x16x32_bf16 v[22:25], v[142:145], v[218:221], v[22:25]
	v_mfma_f32_16x16x32_bf16 v[6:9], v[110:113], v[226:229], v[6:9]
	v_mfma_f32_16x16x32_bf16 v[2:5], v[142:145], v[226:229], v[2:5]
	s_setprio 0
	s_barrier
	s_add_u32 s70, s70, 0x100
	s_addc_u32 s71, s71, 0
	s_cmp_ge_i32 vcc_lo, s51
	s_mov_b64 s[8:9], s[38:39]
	s_mov_b32 s44, vcc_lo
	s_cbranch_scc0 .LBB0_1124
	s_and_b64 vcc, exec, s[12:13]
	s_cbranch_vccz .LBB0_1127
	s_barrier

.LBB0_1508:
	s_add_i32 s39, s35, 2
	s_add_u32 s50, s48, 0xfff80080
	s_addc_u32 s51, s49, -1
	s_add_i32 s72, 0, 0x10000
	s_cmp_eq_u32 s9, s35
	s_cselect_b32 s53, s37, s51
	s_cselect_b32 s52, s36, s50
	s_cselect_b32 s51, s45, s29
	s_cselect_b32 s50, s44, s13
	s_add_i32 s35, 0, 0x14000
	v_add_u32_e32 v160, s72, v152
	v_add_u32_e32 v176, s35, v152
	s_add_i32 m0, s25, 0xc000
	global_load_lds_dwordx4 v144, s[48:49]
	s_add_i32 m0, s25, 0xe000
	s_nop 0
	global_load_lds_dwordx4 v146, s[48:49]
	ds_read_b128 v[136:139], v160
	ds_read_b128 v[148:151], v160 offset:1024
	ds_read_b128 v[156:159], v160 offset:2048
	ds_read_b128 v[160:163], v160 offset:3072
	ds_read_b128 v[164:167], v176
	ds_read_b128 v[168:171], v176 offset:1024
	ds_read_b128 v[172:175], v176 offset:2048
	ds_read_b128 v[184:187], v176 offset:3072
	ds_read_b128 v[188:191], v155
	ds_read_b128 v[192:195], v155 offset:1024
	ds_read_b128 v[196:199], v155 offset:2048
	ds_read_b128 v[200:203], v155 offset:3072
	ds_read_b128 v[214:217], v155 offset:4096
	ds_read_b128 v[218:221], v155 offset:5120
	ds_read_b128 v[222:225], v155 offset:6144
	ds_read_b128 v[226:229], v155 offset:7168
	s_waitcnt vmcnt(8)
	s_waitcnt lgkmcnt(0)
	s_barrier
	s_setprio 1
	s_waitcnt lgkmcnt(0)
	v_mfma_f32_16x16x32_bf16 v[132:135], v[136:139], v[188:191], v[132:135]
	v_mfma_f32_16x16x32_bf16 v[128:131], v[156:159], v[188:191], v[128:131]
	v_mfma_f32_16x16x32_bf16 v[116:119], v[136:139], v[196:199], v[116:119]
	v_mfma_f32_16x16x32_bf16 v[112:115], v[156:159], v[196:199], v[112:115]
	v_mfma_f32_16x16x32_bf16 v[100:103], v[136:139], v[214:217], v[100:103]
	v_mfma_f32_16x16x32_bf16 v[96:99], v[156:159], v[214:217], v[96:99]
	v_mfma_f32_16x16x32_bf16 v[84:87], v[136:139], v[222:225], v[84:87]
	v_mfma_f32_16x16x32_bf16 v[80:83], v[156:159], v[222:225], v[80:83]
	v_mfma_f32_16x16x32_bf16 v[132:135], v[148:151], v[192:195], v[132:135]
	v_mfma_f32_16x16x32_bf16 v[128:131], v[160:163], v[192:195], v[128:131]
	v_mfma_f32_16x16x32_bf16 v[116:119], v[148:151], v[200:203], v[116:119]
	v_mfma_f32_16x16x32_bf16 v[112:115], v[160:163], v[200:203], v[112:115]
	v_mfma_f32_16x16x32_bf16 v[100:103], v[148:151], v[218:221], v[100:103]
	v_mfma_f32_16x16x32_bf16 v[96:99], v[160:163], v[218:221], v[96:99]
	v_mfma_f32_16x16x32_bf16 v[84:87], v[148:151], v[226:229], v[84:87]
	v_mfma_f32_16x16x32_bf16 v[80:83], v[160:163], v[226:229], v[80:83]
	s_setprio 0
	s_setprio 1
	v_mfma_f32_16x16x32_bf16 v[124:127], v[164:167], v[188:191], v[124:127]
	v_mfma_f32_16x16x32_bf16 v[120:123], v[172:175], v[188:191], v[120:123]
	v_mfma_f32_16x16x32_bf16 v[108:111], v[164:167], v[196:199], v[108:111]
	v_mfma_f32_16x16x32_bf16 v[104:107], v[172:175], v[196:199], v[104:107]
	v_mfma_f32_16x16x32_bf16 v[92:95], v[164:167], v[214:217], v[92:95]
	v_mfma_f32_16x16x32_bf16 v[88:91], v[172:175], v[214:217], v[88:91]
	v_mfma_f32_16x16x32_bf16 v[76:79], v[164:167], v[222:225], v[76:79]
	v_mfma_f32_16x16x32_bf16 v[72:75], v[172:175], v[222:225], v[72:75]
	v_mfma_f32_16x16x32_bf16 v[124:127], v[168:171], v[192:195], v[124:127]
	v_mfma_f32_16x16x32_bf16 v[120:123], v[184:187], v[192:195], v[120:123]
	v_mfma_f32_16x16x32_bf16 v[108:111], v[168:171], v[200:203], v[108:111]
	v_mfma_f32_16x16x32_bf16 v[104:107], v[184:187], v[200:203], v[104:107]
	v_mfma_f32_16x16x32_bf16 v[92:95], v[168:171], v[218:221], v[92:95]
	v_mfma_f32_16x16x32_bf16 v[88:91], v[184:187], v[218:221], v[88:91]
	v_mfma_f32_16x16x32_bf16 v[76:79], v[168:171], v[226:229], v[76:79]
	v_mfma_f32_16x16x32_bf16 v[72:75], v[184:187], v[226:229], v[72:75]
	s_setprio 0
	s_barrier
	s_add_u32 s98, s50, s22
	s_addc_u32 s99, s51, s23
	s_add_u32 s100, s52, s22
	s_addc_u32 s101, s53, s23
	s_add_i32 s72, s72, s20
	s_mov_b32 m0, s72
	ds_read_b128 v[188:191], v155 offset:16384
	ds_read_b128 v[192:195], v155 offset:17408
	ds_read_b128 v[196:199], v155 offset:18432
	ds_read_b128 v[200:203], v155 offset:19456
	ds_read_b128 v[214:217], v155 offset:20480
	ds_read_b128 v[218:221], v155 offset:21504
	ds_read_b128 v[222:225], v155 offset:22528
	ds_read_b128 v[226:229], v155 offset:23552
	global_load_lds_dwordx4 v34, s[50:51]
	s_add_i32 m0, s72, 0x2000
	s_add_u32 s72, s50, 0x80000
	s_addc_u32 s73, s51, 0
	s_add_i32 s35, s35, s20
	global_load_lds_dwordx4 v142, s[50:51]
	s_mov_b32 m0, s35
	global_load_lds_dwordx4 v34, s[72:73]
	s_add_i32 m0, s35, 0x2000
	s_nop 0
	global_load_lds_dwordx4 v142, s[72:73]
	s_mov_b32 m0, s25
	s_nop 0
	global_load_lds_dwordx4 v14, s[52:53]
	s_mov_b32 m0, s26
	s_nop 0
	global_load_lds_dwordx4 v140, s[52:53]
	s_waitcnt vmcnt(8)
	s_waitcnt lgkmcnt(0)
	s_barrier
	s_setprio 1
	s_waitcnt lgkmcnt(0)
	v_mfma_f32_16x16x32_bf16 v[68:71], v[136:139], v[188:191], v[68:71]
	v_mfma_f32_16x16x32_bf16 v[64:67], v[156:159], v[188:191], v[64:67]
	v_mfma_f32_16x16x32_bf16 v[52:55], v[136:139], v[196:199], v[52:55]
	v_mfma_f32_16x16x32_bf16 v[48:51], v[156:159], v[196:199], v[48:51]
	v_mfma_f32_16x16x32_bf16 v[36:39], v[136:139], v[214:217], v[36:39]
	v_mfma_f32_16x16x32_bf16 v[30:33], v[156:159], v[214:217], v[30:33]
	v_mfma_f32_16x16x32_bf16 v[18:21], v[136:139], v[222:225], v[18:21]
	v_mfma_f32_16x16x32_bf16 v[10:13], v[156:159], v[222:225], v[10:13]
	v_mfma_f32_16x16x32_bf16 v[68:71], v[148:151], v[192:195], v[68:71]
	v_mfma_f32_16x16x32_bf16 v[64:67], v[160:163], v[192:195], v[64:67]
	v_mfma_f32_16x16x32_bf16 v[52:55], v[148:151], v[200:203], v[52:55]
	v_mfma_f32_16x16x32_bf16 v[48:51], v[160:163], v[200:203], v[48:51]
	v_mfma_f32_16x16x32_bf16 v[36:39], v[148:151], v[218:221], v[36:39]
	v_mfma_f32_16x16x32_bf16 v[30:33], v[160:163], v[218:221], v[30:33]
	v_mfma_f32_16x16x32_bf16 v[18:21], v[148:151], v[226:229], v[18:21]
	v_mfma_f32_16x16x32_bf16 v[10:13], v[160:163], v[226:229], v[10:13]
	s_setprio 0
	s_setprio 1
	v_mfma_f32_16x16x32_bf16 v[60:63], v[164:167], v[188:191], v[60:63]
	v_mfma_f32_16x16x32_bf16 v[56:59], v[172:175], v[188:191], v[56:59]
	v_mfma_f32_16x16x32_bf16 v[44:47], v[164:167], v[196:199], v[44:47]
	v_mfma_f32_16x16x32_bf16 v[40:43], v[172:175], v[196:199], v[40:43]
	v_mfma_f32_16x16x32_bf16 v[26:29], v[164:167], v[214:217], v[26:29]
	v_mfma_f32_16x16x32_bf16 v[22:25], v[172:175], v[214:217], v[22:25]
	v_mfma_f32_16x16x32_bf16 v[6:9], v[164:167], v[222:225], v[6:9]
	v_mfma_f32_16x16x32_bf16 v[2:5], v[172:175], v[222:225], v[2:5]
	v_mfma_f32_16x16x32_bf16 v[60:63], v[168:171], v[192:195], v[60:63]
	v_mfma_f32_16x16x32_bf16 v[56:59], v[184:187], v[192:195], v[56:59]
	v_mfma_f32_16x16x32_bf16 v[44:47], v[168:171], v[200:203], v[44:47]
	v_mfma_f32_16x16x32_bf16 v[40:43], v[184:187], v[200:203], v[40:43]
	v_mfma_f32_16x16x32_bf16 v[26:29], v[168:171], v[218:221], v[26:29]
	v_mfma_f32_16x16x32_bf16 v[22:25], v[184:187], v[218:221], v[22:25]
	v_mfma_f32_16x16x32_bf16 v[6:9], v[168:171], v[226:229], v[6:9]
	v_mfma_f32_16x16x32_bf16 v[2:5], v[184:187], v[226:229], v[2:5]
	s_setprio 0
	s_barrier
	s_add_i32 s35, 0, 0x18000
	s_add_i32 s72, 0, 0x1c000
	v_add_u32_e32 v160, s35, v152
	v_add_u32_e32 v183, s72, v152
	s_add_u32 s52, s52, 0x80000
	s_addc_u32 s53, s53, 0
	s_mov_b32 m0, s27
	global_load_lds_dwordx4 v14, s[52:53]
	s_mov_b32 m0, s31
	s_nop 0
	global_load_lds_dwordx4 v140, s[52:53]
	ds_read_b128 v[136:139], v160
	ds_read_b128 v[148:151], v160 offset:1024
	ds_read_b128 v[156:159], v160 offset:2048
	ds_read_b128 v[160:163], v160 offset:3072
	ds_read_b128 v[164:167], v183
	ds_read_b128 v[168:171], v183 offset:1024
	ds_read_b128 v[172:175], v183 offset:2048
	ds_read_b128 v[184:187], v183 offset:3072
	ds_read_b128 v[188:191], v155 offset:32768
	ds_read_b128 v[192:195], v155 offset:33792
	ds_read_b128 v[196:199], v155 offset:34816
	ds_read_b128 v[200:203], v155 offset:35840
	ds_read_b128 v[214:217], v155 offset:36864
	ds_read_b128 v[218:221], v155 offset:37888
	ds_read_b128 v[222:225], v155 offset:38912
	ds_read_b128 v[226:229], v155 offset:39936
	s_waitcnt vmcnt(8)
	s_waitcnt lgkmcnt(0)
	s_barrier
	s_setprio 1
	s_waitcnt lgkmcnt(0)
	v_mfma_f32_16x16x32_bf16 v[132:135], v[136:139], v[188:191], v[132:135]
	v_mfma_f32_16x16x32_bf16 v[128:131], v[156:159], v[188:191], v[128:131]
	v_mfma_f32_16x16x32_bf16 v[116:119], v[136:139], v[196:199], v[116:119]
	v_mfma_f32_16x16x32_bf16 v[112:115], v[156:159], v[196:199], v[112:115]
	v_mfma_f32_16x16x32_bf16 v[100:103], v[136:139], v[214:217], v[100:103]
	v_mfma_f32_16x16x32_bf16 v[96:99], v[156:159], v[214:217], v[96:99]
	v_mfma_f32_16x16x32_bf16 v[84:87], v[136:139], v[222:225], v[84:87]
	v_mfma_f32_16x16x32_bf16 v[80:83], v[156:159], v[222:225], v[80:83]
	v_mfma_f32_16x16x32_bf16 v[132:135], v[148:151], v[192:195], v[132:135]
	v_mfma_f32_16x16x32_bf16 v[128:131], v[160:163], v[192:195], v[128:131]
	v_mfma_f32_16x16x32_bf16 v[116:119], v[148:151], v[200:203], v[116:119]
	v_mfma_f32_16x16x32_bf16 v[112:115], v[160:163], v[200:203], v[112:115]
	v_mfma_f32_16x16x32_bf16 v[100:103], v[148:151], v[218:221], v[100:103]
	v_mfma_f32_16x16x32_bf16 v[96:99], v[160:163], v[218:221], v[96:99]
	v_mfma_f32_16x16x32_bf16 v[84:87], v[148:151], v[226:229], v[84:87]
	v_mfma_f32_16x16x32_bf16 v[80:83], v[160:163], v[226:229], v[80:83]
	s_setprio 0
	s_setprio 1
	v_mfma_f32_16x16x32_bf16 v[124:127], v[164:167], v[188:191], v[124:127]
	v_mfma_f32_16x16x32_bf16 v[120:123], v[172:175], v[188:191], v[120:123]
	v_mfma_f32_16x16x32_bf16 v[108:111], v[164:167], v[196:199], v[108:111]
	v_mfma_f32_16x16x32_bf16 v[104:107], v[172:175], v[196:199], v[104:107]
	v_mfma_f32_16x16x32_bf16 v[92:95], v[164:167], v[214:217], v[92:95]
	v_mfma_f32_16x16x32_bf16 v[88:91], v[172:175], v[214:217], v[88:91]
	v_mfma_f32_16x16x32_bf16 v[76:79], v[164:167], v[222:225], v[76:79]
	v_mfma_f32_16x16x32_bf16 v[72:75], v[172:175], v[222:225], v[72:75]
	v_mfma_f32_16x16x32_bf16 v[124:127], v[168:171], v[192:195], v[124:127]
	v_mfma_f32_16x16x32_bf16 v[120:123], v[184:187], v[192:195], v[120:123]
	v_mfma_f32_16x16x32_bf16 v[108:111], v[168:171], v[200:203], v[108:111]
	v_mfma_f32_16x16x32_bf16 v[104:107], v[184:187], v[200:203], v[104:107]
	v_mfma_f32_16x16x32_bf16 v[92:95], v[168:171], v[218:221], v[92:95]
	v_mfma_f32_16x16x32_bf16 v[88:91], v[184:187], v[218:221], v[88:91]
	v_mfma_f32_16x16x32_bf16 v[76:79], v[168:171], v[226:229], v[76:79]
	v_mfma_f32_16x16x32_bf16 v[72:75], v[184:187], v[226:229], v[72:75]
	s_setprio 0
	s_barrier
	s_add_i32 s35, s35, s20
	s_mov_b32 m0, s35
	ds_read_b128 v[188:191], v155 offset:49152
	ds_read_b128 v[192:195], v155 offset:50176
	ds_read_b128 v[196:199], v155 offset:51200
	ds_read_b128 v[200:203], v155 offset:52224
	ds_read_b128 v[214:217], v155 offset:53248
	ds_read_b128 v[218:221], v155 offset:54272
	ds_read_b128 v[222:225], v155 offset:55296
	ds_read_b128 v[226:229], v155 offset:56320
	global_load_lds_dwordx4 v34, s[98:99]
	s_add_i32 m0, s35, 0x2000
	s_add_u32 s50, s50, 0x80080
	s_addc_u32 s51, s51, 0
	s_add_i32 s35, s72, s20
	global_load_lds_dwordx4 v142, s[98:99]
	s_mov_b32 m0, s35
	s_nop 0
	global_load_lds_dwordx4 v34, s[50:51]
	s_add_i32 m0, s35, 0x2000
	s_nop 0
	global_load_lds_dwordx4 v142, s[50:51]
	s_mov_b32 m0, s60
	s_nop 0
	global_load_lds_dwordx4 v14, s[100:101]
	s_mov_b32 m0, s61
	s_nop 0
	global_load_lds_dwordx4 v140, s[100:101]
	s_waitcnt vmcnt(8)
	s_waitcnt lgkmcnt(0)
	s_barrier
	s_setprio 1
	s_waitcnt lgkmcnt(0)
	v_mfma_f32_16x16x32_bf16 v[68:71], v[136:139], v[188:191], v[68:71]
	v_mfma_f32_16x16x32_bf16 v[64:67], v[156:159], v[188:191], v[64:67]
	v_mfma_f32_16x16x32_bf16 v[52:55], v[136:139], v[196:199], v[52:55]
	v_mfma_f32_16x16x32_bf16 v[48:51], v[156:159], v[196:199], v[48:51]
	v_mfma_f32_16x16x32_bf16 v[36:39], v[136:139], v[214:217], v[36:39]
	v_mfma_f32_16x16x32_bf16 v[30:33], v[156:159], v[214:217], v[30:33]
	v_mfma_f32_16x16x32_bf16 v[18:21], v[136:139], v[222:225], v[18:21]
	v_mfma_f32_16x16x32_bf16 v[10:13], v[156:159], v[222:225], v[10:13]
	v_mfma_f32_16x16x32_bf16 v[68:71], v[148:151], v[192:195], v[68:71]
	v_mfma_f32_16x16x32_bf16 v[64:67], v[160:163], v[192:195], v[64:67]
	v_mfma_f32_16x16x32_bf16 v[52:55], v[148:151], v[200:203], v[52:55]
	v_mfma_f32_16x16x32_bf16 v[48:51], v[160:163], v[200:203], v[48:51]
	v_mfma_f32_16x16x32_bf16 v[36:39], v[148:151], v[218:221], v[36:39]
	v_mfma_f32_16x16x32_bf16 v[30:33], v[160:163], v[218:221], v[30:33]
	v_mfma_f32_16x16x32_bf16 v[18:21], v[148:151], v[226:229], v[18:21]
	v_mfma_f32_16x16x32_bf16 v[10:13], v[160:163], v[226:229], v[10:13]
	s_setprio 0
	s_setprio 1
	v_mfma_f32_16x16x32_bf16 v[60:63], v[164:167], v[188:191], v[60:63]
	v_mfma_f32_16x16x32_bf16 v[56:59], v[172:175], v[188:191], v[56:59]
	v_mfma_f32_16x16x32_bf16 v[44:47], v[164:167], v[196:199], v[44:47]
	v_mfma_f32_16x16x32_bf16 v[40:43], v[172:175], v[196:199], v[40:43]
	v_mfma_f32_16x16x32_bf16 v[26:29], v[164:167], v[214:217], v[26:29]
	v_mfma_f32_16x16x32_bf16 v[22:25], v[172:175], v[214:217], v[22:25]
	v_mfma_f32_16x16x32_bf16 v[6:9], v[164:167], v[222:225], v[6:9]
	v_mfma_f32_16x16x32_bf16 v[2:5], v[172:175], v[222:225], v[2:5]
	v_mfma_f32_16x16x32_bf16 v[60:63], v[168:171], v[192:195], v[60:63]
	v_mfma_f32_16x16x32_bf16 v[56:59], v[184:187], v[192:195], v[56:59]
	v_mfma_f32_16x16x32_bf16 v[44:47], v[168:171], v[200:203], v[44:47]
	v_mfma_f32_16x16x32_bf16 v[40:43], v[184:187], v[200:203], v[40:43]
	v_mfma_f32_16x16x32_bf16 v[26:29], v[168:171], v[218:221], v[26:29]
	v_mfma_f32_16x16x32_bf16 v[22:25], v[184:187], v[218:221], v[22:25]
	v_mfma_f32_16x16x32_bf16 v[6:9], v[168:171], v[226:229], v[6:9]
	v_mfma_f32_16x16x32_bf16 v[2:5], v[184:187], v[226:229], v[2:5]
	s_setprio 0
	s_barrier
	s_add_u32 s48, s48, 0x100
	s_addc_u32 s49, s49, 0
	s_add_u32 s13, s13, 0x100
	s_addc_u32 s29, s29, 0
	s_cmp_ge_i32 s39, s71
	s_mov_b32 s35, s39
	s_cbranch_scc0 .LBB0_1508
	s_and_b64 vcc, exec, s[10:11]
	s_cbranch_vccz .LBB0_1511

.LBB0_1664:
	s_add_u32 s44, s42, 0xfff80080
	s_addc_u32 s45, s43, -1
	s_add_i32 s64, 0, 0x10000
	s_cmp_eq_u32 s61, 28
	s_cselect_b32 s47, s29, s45
	s_cselect_b32 s46, s53, s44
	v_add_u32_e32 v151, s64, v141
	s_cselect_b32 s45, s13, s60
	s_cselect_b32 s44, s54, s55
	s_add_i32 s67, 0, 0x14000
	s_add_i32 m0, s25, 0xc000
	global_load_lds_dwordx4 v142, s[42:43]
	s_add_i32 m0, s25, 0xe000
	s_nop 0
	global_load_lds_dwordx4 v144, s[42:43]
	ds_read_b128 v[162:165], v151
	ds_read_b128 v[166:169], v151 offset:1024
	ds_read_b128 v[170:173], v151 offset:2048
	ds_read_b128 v[174:177], v151 offset:3072
	v_add_u32_e32 v151, s67, v141
	ds_read_b128 v[184:187], v151
	ds_read_b128 v[188:191], v151 offset:1024
	ds_read_b128 v[192:195], v151 offset:2048
	ds_read_b128 v[196:199], v151 offset:3072
	ds_read_b128 v[200:203], v149
	ds_read_b128 v[214:217], v149 offset:1024
	ds_read_b128 v[218:221], v149 offset:2048
	ds_read_b128 v[222:225], v149 offset:3072
	ds_read_b128 v[226:229], v149 offset:4096
	ds_read_b128 v[230:233], v149 offset:5120
	ds_read_b128 v[234:237], v149 offset:6144
	ds_read_b128 v[238:241], v149 offset:7168
	s_waitcnt vmcnt(8)
	s_waitcnt lgkmcnt(0)
	s_barrier
	s_setprio 1
	s_waitcnt lgkmcnt(0)
	v_mfma_f32_16x16x32_bf16 v[132:135], v[162:165], v[200:203], v[132:135]
	v_mfma_f32_16x16x32_bf16 v[128:131], v[170:173], v[200:203], v[128:131]
	v_mfma_f32_16x16x32_bf16 v[116:119], v[162:165], v[218:221], v[116:119]
	v_mfma_f32_16x16x32_bf16 v[112:115], v[170:173], v[218:221], v[112:115]
	v_mfma_f32_16x16x32_bf16 v[100:103], v[162:165], v[226:229], v[100:103]
	v_mfma_f32_16x16x32_bf16 v[96:99], v[170:173], v[226:229], v[96:99]
	v_mfma_f32_16x16x32_bf16 v[84:87], v[162:165], v[234:237], v[84:87]
	v_mfma_f32_16x16x32_bf16 v[80:83], v[170:173], v[234:237], v[80:83]
	v_mfma_f32_16x16x32_bf16 v[132:135], v[166:169], v[214:217], v[132:135]
	v_mfma_f32_16x16x32_bf16 v[128:131], v[174:177], v[214:217], v[128:131]
	v_mfma_f32_16x16x32_bf16 v[116:119], v[166:169], v[222:225], v[116:119]
	v_mfma_f32_16x16x32_bf16 v[112:115], v[174:177], v[222:225], v[112:115]
	v_mfma_f32_16x16x32_bf16 v[100:103], v[166:169], v[230:233], v[100:103]
	v_mfma_f32_16x16x32_bf16 v[96:99], v[174:177], v[230:233], v[96:99]
	v_mfma_f32_16x16x32_bf16 v[84:87], v[166:169], v[238:241], v[84:87]
	v_mfma_f32_16x16x32_bf16 v[80:83], v[174:177], v[238:241], v[80:83]
	s_setprio 0
	s_setprio 1
	v_mfma_f32_16x16x32_bf16 v[124:127], v[184:187], v[200:203], v[124:127]
	v_mfma_f32_16x16x32_bf16 v[120:123], v[192:195], v[200:203], v[120:123]
	v_mfma_f32_16x16x32_bf16 v[108:111], v[184:187], v[218:221], v[108:111]
	v_mfma_f32_16x16x32_bf16 v[104:107], v[192:195], v[218:221], v[104:107]
	v_mfma_f32_16x16x32_bf16 v[92:95], v[184:187], v[226:229], v[92:95]
	v_mfma_f32_16x16x32_bf16 v[88:91], v[192:195], v[226:229], v[88:91]
	v_mfma_f32_16x16x32_bf16 v[76:79], v[184:187], v[234:237], v[76:79]
	v_mfma_f32_16x16x32_bf16 v[72:75], v[192:195], v[234:237], v[72:75]
	v_mfma_f32_16x16x32_bf16 v[124:127], v[188:191], v[214:217], v[124:127]
	v_mfma_f32_16x16x32_bf16 v[120:123], v[196:199], v[214:217], v[120:123]
	v_mfma_f32_16x16x32_bf16 v[108:111], v[188:191], v[222:225], v[108:111]
	v_mfma_f32_16x16x32_bf16 v[104:107], v[196:199], v[222:225], v[104:107]
	v_mfma_f32_16x16x32_bf16 v[92:95], v[188:191], v[230:233], v[92:95]
	v_mfma_f32_16x16x32_bf16 v[88:91], v[196:199], v[230:233], v[88:91]
	v_mfma_f32_16x16x32_bf16 v[76:79], v[188:191], v[238:241], v[76:79]
	v_mfma_f32_16x16x32_bf16 v[72:75], v[196:199], v[238:241], v[72:75]
	s_setprio 0
	s_barrier
	s_add_u32 s98, s44, s22
	s_addc_u32 s99, s45, s23
	s_add_u32 s100, s46, s22
	s_addc_u32 s101, s47, s23
	s_add_i32 s64, s64, s20
	s_mov_b32 m0, s64
	ds_read_b128 v[200:203], v149 offset:16384
	ds_read_b128 v[214:217], v149 offset:17408
	ds_read_b128 v[218:221], v149 offset:18432
	ds_read_b128 v[222:225], v149 offset:19456
	ds_read_b128 v[226:229], v149 offset:20480
	ds_read_b128 v[230:233], v149 offset:21504
	ds_read_b128 v[234:237], v149 offset:22528
	ds_read_b128 v[238:241], v149 offset:23552
	global_load_lds_dwordx4 v34, s[44:45]
	s_add_i32 m0, s64, 0x2000
	s_add_u32 s64, s44, 0x80000
	s_addc_u32 s65, s45, 0
	s_add_i32 s67, s67, s20
	global_load_lds_dwordx4 v14, s[44:45]
	s_mov_b32 m0, s67
	global_load_lds_dwordx4 v34, s[64:65]
	s_add_i32 m0, s67, 0x2000
	s_nop 0
	global_load_lds_dwordx4 v14, s[64:65]
	s_mov_b32 m0, s25
	s_nop 0
	global_load_lds_dwordx4 v138, s[46:47]
	s_mov_b32 m0, s26
	s_nop 0
	global_load_lds_dwordx4 v136, s[46:47]
	s_waitcnt vmcnt(8)
	s_waitcnt lgkmcnt(0)
	s_barrier
	s_setprio 1
	s_waitcnt lgkmcnt(0)
	v_mfma_f32_16x16x32_bf16 v[68:71], v[162:165], v[200:203], v[68:71]
	v_mfma_f32_16x16x32_bf16 v[64:67], v[170:173], v[200:203], v[64:67]
	v_mfma_f32_16x16x32_bf16 v[52:55], v[162:165], v[218:221], v[52:55]
	v_mfma_f32_16x16x32_bf16 v[48:51], v[170:173], v[218:221], v[48:51]
	v_mfma_f32_16x16x32_bf16 v[36:39], v[162:165], v[226:229], v[36:39]
	v_mfma_f32_16x16x32_bf16 v[30:33], v[170:173], v[226:229], v[30:33]
	v_mfma_f32_16x16x32_bf16 v[18:21], v[162:165], v[234:237], v[18:21]
	v_mfma_f32_16x16x32_bf16 v[10:13], v[170:173], v[234:237], v[10:13]
	v_mfma_f32_16x16x32_bf16 v[68:71], v[166:169], v[214:217], v[68:71]
	v_mfma_f32_16x16x32_bf16 v[64:67], v[174:177], v[214:217], v[64:67]
	v_mfma_f32_16x16x32_bf16 v[52:55], v[166:169], v[222:225], v[52:55]
	v_mfma_f32_16x16x32_bf16 v[48:51], v[174:177], v[222:225], v[48:51]
	v_mfma_f32_16x16x32_bf16 v[36:39], v[166:169], v[230:233], v[36:39]
	v_mfma_f32_16x16x32_bf16 v[30:33], v[174:177], v[230:233], v[30:33]
	v_mfma_f32_16x16x32_bf16 v[18:21], v[166:169], v[238:241], v[18:21]
	v_mfma_f32_16x16x32_bf16 v[10:13], v[174:177], v[238:241], v[10:13]
	s_setprio 0
	s_setprio 1
	v_mfma_f32_16x16x32_bf16 v[60:63], v[184:187], v[200:203], v[60:63]
	v_mfma_f32_16x16x32_bf16 v[56:59], v[192:195], v[200:203], v[56:59]
	v_mfma_f32_16x16x32_bf16 v[44:47], v[184:187], v[218:221], v[44:47]
	v_mfma_f32_16x16x32_bf16 v[40:43], v[192:195], v[218:221], v[40:43]
	v_mfma_f32_16x16x32_bf16 v[26:29], v[184:187], v[226:229], v[26:29]
	v_mfma_f32_16x16x32_bf16 v[22:25], v[192:195], v[226:229], v[22:25]
	v_mfma_f32_16x16x32_bf16 v[6:9], v[184:187], v[234:237], v[6:9]
	v_mfma_f32_16x16x32_bf16 v[2:5], v[192:195], v[234:237], v[2:5]
	v_mfma_f32_16x16x32_bf16 v[60:63], v[188:191], v[214:217], v[60:63]
	v_mfma_f32_16x16x32_bf16 v[56:59], v[196:199], v[214:217], v[56:59]
	v_mfma_f32_16x16x32_bf16 v[44:47], v[188:191], v[222:225], v[44:47]
	v_mfma_f32_16x16x32_bf16 v[40:43], v[196:199], v[222:225], v[40:43]
	v_mfma_f32_16x16x32_bf16 v[26:29], v[188:191], v[230:233], v[26:29]
	v_mfma_f32_16x16x32_bf16 v[22:25], v[196:199], v[230:233], v[22:25]
	v_mfma_f32_16x16x32_bf16 v[6:9], v[188:191], v[238:241], v[6:9]
	v_mfma_f32_16x16x32_bf16 v[2:5], v[196:199], v[238:241], v[2:5]
	s_setprio 0
	s_barrier
	s_add_i32 s64, 0, 0x18000
	v_add_u32_e32 v151, s64, v141
	s_add_i32 s65, 0, 0x1c000
	s_add_u32 s46, s46, 0x80000
	s_addc_u32 s47, s47, 0
	s_mov_b32 m0, s27
	global_load_lds_dwordx4 v138, s[46:47]
	s_mov_b32 m0, s31
	s_nop 0
	global_load_lds_dwordx4 v136, s[46:47]
	ds_read_b128 v[162:165], v151
	ds_read_b128 v[166:169], v151 offset:1024
	ds_read_b128 v[170:173], v151 offset:2048
	ds_read_b128 v[174:177], v151 offset:3072
	v_add_u32_e32 v151, s65, v141
	ds_read_b128 v[184:187], v151
	ds_read_b128 v[188:191], v151 offset:1024
	ds_read_b128 v[192:195], v151 offset:2048
	ds_read_b128 v[196:199], v151 offset:3072
	ds_read_b128 v[200:203], v149 offset:32768
	ds_read_b128 v[214:217], v149 offset:33792
	ds_read_b128 v[218:221], v149 offset:34816
	ds_read_b128 v[222:225], v149 offset:35840
	ds_read_b128 v[226:229], v149 offset:36864
	ds_read_b128 v[230:233], v149 offset:37888
	ds_read_b128 v[234:237], v149 offset:38912
	ds_read_b128 v[238:241], v149 offset:39936
	s_waitcnt vmcnt(8)
	s_waitcnt lgkmcnt(0)
	s_barrier
	s_setprio 1
	s_waitcnt lgkmcnt(0)
	v_mfma_f32_16x16x32_bf16 v[132:135], v[162:165], v[200:203], v[132:135]
	v_mfma_f32_16x16x32_bf16 v[128:131], v[170:173], v[200:203], v[128:131]
	v_mfma_f32_16x16x32_bf16 v[116:119], v[162:165], v[218:221], v[116:119]
	v_mfma_f32_16x16x32_bf16 v[112:115], v[170:173], v[218:221], v[112:115]
	v_mfma_f32_16x16x32_bf16 v[100:103], v[162:165], v[226:229], v[100:103]
	v_mfma_f32_16x16x32_bf16 v[96:99], v[170:173], v[226:229], v[96:99]
	v_mfma_f32_16x16x32_bf16 v[84:87], v[162:165], v[234:237], v[84:87]
	v_mfma_f32_16x16x32_bf16 v[80:83], v[170:173], v[234:237], v[80:83]
	v_mfma_f32_16x16x32_bf16 v[132:135], v[166:169], v[214:217], v[132:135]
	v_mfma_f32_16x16x32_bf16 v[128:131], v[174:177], v[214:217], v[128:131]
	v_mfma_f32_16x16x32_bf16 v[116:119], v[166:169], v[222:225], v[116:119]
	v_mfma_f32_16x16x32_bf16 v[112:115], v[174:177], v[222:225], v[112:115]
	v_mfma_f32_16x16x32_bf16 v[100:103], v[166:169], v[230:233], v[100:103]
	v_mfma_f32_16x16x32_bf16 v[96:99], v[174:177], v[230:233], v[96:99]
	v_mfma_f32_16x16x32_bf16 v[84:87], v[166:169], v[238:241], v[84:87]
	v_mfma_f32_16x16x32_bf16 v[80:83], v[174:177], v[238:241], v[80:83]
	s_setprio 0
	s_setprio 1
	v_mfma_f32_16x16x32_bf16 v[124:127], v[184:187], v[200:203], v[124:127]
	v_mfma_f32_16x16x32_bf16 v[120:123], v[192:195], v[200:203], v[120:123]
	v_mfma_f32_16x16x32_bf16 v[108:111], v[184:187], v[218:221], v[108:111]
	v_mfma_f32_16x16x32_bf16 v[104:107], v[192:195], v[218:221], v[104:107]
	v_mfma_f32_16x16x32_bf16 v[92:95], v[184:187], v[226:229], v[92:95]
	v_mfma_f32_16x16x32_bf16 v[88:91], v[192:195], v[226:229], v[88:91]
	v_mfma_f32_16x16x32_bf16 v[76:79], v[184:187], v[234:237], v[76:79]
	v_mfma_f32_16x16x32_bf16 v[72:75], v[192:195], v[234:237], v[72:75]
	v_mfma_f32_16x16x32_bf16 v[124:127], v[188:191], v[214:217], v[124:127]
	v_mfma_f32_16x16x32_bf16 v[120:123], v[196:199], v[214:217], v[120:123]
	v_mfma_f32_16x16x32_bf16 v[108:111], v[188:191], v[222:225], v[108:111]
	v_mfma_f32_16x16x32_bf16 v[104:107], v[196:199], v[222:225], v[104:107]
	v_mfma_f32_16x16x32_bf16 v[92:95], v[188:191], v[230:233], v[92:95]
	v_mfma_f32_16x16x32_bf16 v[88:91], v[196:199], v[230:233], v[88:91]
	v_mfma_f32_16x16x32_bf16 v[76:79], v[188:191], v[238:241], v[76:79]
	v_mfma_f32_16x16x32_bf16 v[72:75], v[196:199], v[238:241], v[72:75]
	s_setprio 0
	s_barrier
	s_add_i32 s46, s64, s20
	s_mov_b32 m0, s46
	ds_read_b128 v[200:203], v149 offset:49152
	ds_read_b128 v[214:217], v149 offset:50176
	ds_read_b128 v[218:221], v149 offset:51200
	ds_read_b128 v[222:225], v149 offset:52224
	ds_read_b128 v[226:229], v149 offset:53248
	ds_read_b128 v[230:233], v149 offset:54272
	ds_read_b128 v[234:237], v149 offset:55296
	ds_read_b128 v[238:241], v149 offset:56320
	global_load_lds_dwordx4 v34, s[98:99]
	s_add_i32 m0, s46, 0x2000
	s_add_u32 s44, s44, 0x80080
	s_addc_u32 s45, s45, 0
	s_add_i32 s46, s65, s20
	global_load_lds_dwordx4 v14, s[98:99]
	s_mov_b32 m0, s46
	s_nop 0
	global_load_lds_dwordx4 v34, s[44:45]
	s_add_i32 m0, s46, 0x2000
	s_nop 0
	global_load_lds_dwordx4 v14, s[44:45]
	s_mov_b32 m0, s48
	s_nop 0
	global_load_lds_dwordx4 v138, s[100:101]
	s_mov_b32 m0, s49
	s_nop 0
	global_load_lds_dwordx4 v136, s[100:101]
	s_waitcnt vmcnt(8)
	s_waitcnt lgkmcnt(0)
	s_barrier
	s_setprio 1
	s_waitcnt lgkmcnt(0)
	v_mfma_f32_16x16x32_bf16 v[68:71], v[162:165], v[200:203], v[68:71]
	v_mfma_f32_16x16x32_bf16 v[64:67], v[170:173], v[200:203], v[64:67]
	v_mfma_f32_16x16x32_bf16 v[52:55], v[162:165], v[218:221], v[52:55]
	v_mfma_f32_16x16x32_bf16 v[48:51], v[170:173], v[218:221], v[48:51]
	v_mfma_f32_16x16x32_bf16 v[36:39], v[162:165], v[226:229], v[36:39]
	v_mfma_f32_16x16x32_bf16 v[30:33], v[170:173], v[226:229], v[30:33]
	v_mfma_f32_16x16x32_bf16 v[18:21], v[162:165], v[234:237], v[18:21]
	v_mfma_f32_16x16x32_bf16 v[10:13], v[170:173], v[234:237], v[10:13]
	v_mfma_f32_16x16x32_bf16 v[68:71], v[166:169], v[214:217], v[68:71]
	v_mfma_f32_16x16x32_bf16 v[64:67], v[174:177], v[214:217], v[64:67]
	v_mfma_f32_16x16x32_bf16 v[52:55], v[166:169], v[222:225], v[52:55]
	v_mfma_f32_16x16x32_bf16 v[48:51], v[174:177], v[222:225], v[48:51]
	v_mfma_f32_16x16x32_bf16 v[36:39], v[166:169], v[230:233], v[36:39]
	v_mfma_f32_16x16x32_bf16 v[30:33], v[174:177], v[230:233], v[30:33]
	v_mfma_f32_16x16x32_bf16 v[18:21], v[166:169], v[238:241], v[18:21]
	v_mfma_f32_16x16x32_bf16 v[10:13], v[174:177], v[238:241], v[10:13]
	s_setprio 0
	s_setprio 1
	v_mfma_f32_16x16x32_bf16 v[60:63], v[184:187], v[200:203], v[60:63]
	v_mfma_f32_16x16x32_bf16 v[56:59], v[192:195], v[200:203], v[56:59]
	v_mfma_f32_16x16x32_bf16 v[44:47], v[184:187], v[218:221], v[44:47]
	v_mfma_f32_16x16x32_bf16 v[40:43], v[192:195], v[218:221], v[40:43]
	v_mfma_f32_16x16x32_bf16 v[26:29], v[184:187], v[226:229], v[26:29]
	v_mfma_f32_16x16x32_bf16 v[22:25], v[192:195], v[226:229], v[22:25]
	v_mfma_f32_16x16x32_bf16 v[6:9], v[184:187], v[234:237], v[6:9]
	v_mfma_f32_16x16x32_bf16 v[2:5], v[192:195], v[234:237], v[2:5]
	v_mfma_f32_16x16x32_bf16 v[60:63], v[188:191], v[214:217], v[60:63]
	v_mfma_f32_16x16x32_bf16 v[56:59], v[196:199], v[214:217], v[56:59]
	v_mfma_f32_16x16x32_bf16 v[44:47], v[188:191], v[222:225], v[44:47]
	v_mfma_f32_16x16x32_bf16 v[40:43], v[196:199], v[222:225], v[40:43]
	v_mfma_f32_16x16x32_bf16 v[26:29], v[188:191], v[230:233], v[26:29]
	v_mfma_f32_16x16x32_bf16 v[22:25], v[196:199], v[230:233], v[22:25]
	v_mfma_f32_16x16x32_bf16 v[6:9], v[188:191], v[238:241], v[6:9]
	v_mfma_f32_16x16x32_bf16 v[2:5], v[196:199], v[238:241], v[2:5]
	s_setprio 0
	s_barrier
	s_add_i32 s61, s61, 2
	s_add_u32 s42, s42, 0x100
	s_addc_u32 s43, s43, 0
	s_add_u32 s55, s55, 0x100
	s_addc_u32 s60, s60, 0
	s_cmp_gt_u32 s61, 29
	s_cbranch_scc0 .LBB0_1664
	s_and_b64 vcc, exec, s[10:11]
	s_cbranch_vccz .LBB0_1667
	s_barrier

.LBB0_1764:
	s_add_i32 vcc_lo, s44, 2
	s_add_u32 s42, s36, 0x100
	s_addc_u32 s43, s37, 0
	s_add_i32 s72, 0, 0x10000
	s_cmp_eq_u32 s11, s44
	s_cselect_b32 s47, s13, s43
	s_cselect_b32 s46, s12, s42
	s_cselect_b32 s45, s29, s71
	s_cselect_b32 s44, s28, s70
	s_add_i32 s73, 0, 0x14000
	v_add_u32_e32 v160, s72, v152
	v_add_u32_e32 v176, s73, v152
	s_add_i32 m0, s25, 0xc000
	global_load_lds_dwordx4 v144, s[36:37]
	s_add_i32 m0, s25, 0xe000
	s_nop 0
	global_load_lds_dwordx4 v146, s[36:37]
	ds_read_b128 v[136:139], v160
	ds_read_b128 v[148:151], v160 offset:1024
	ds_read_b128 v[156:159], v160 offset:2048
	ds_read_b128 v[160:163], v160 offset:3072
	ds_read_b128 v[164:167], v176
	ds_read_b128 v[168:171], v176 offset:1024
	ds_read_b128 v[172:175], v176 offset:2048
	ds_read_b128 v[184:187], v176 offset:3072
	ds_read_b128 v[188:191], v155
	ds_read_b128 v[192:195], v155 offset:1024
	ds_read_b128 v[196:199], v155 offset:2048
	ds_read_b128 v[200:203], v155 offset:3072
	ds_read_b128 v[214:217], v155 offset:4096
	ds_read_b128 v[218:221], v155 offset:5120
	ds_read_b128 v[222:225], v155 offset:6144
	ds_read_b128 v[226:229], v155 offset:7168
	s_waitcnt vmcnt(8)
	s_waitcnt lgkmcnt(0)
	s_barrier
	s_setprio 1
	s_waitcnt lgkmcnt(0)
	v_mfma_f32_16x16x32_bf16 v[132:135], v[136:139], v[188:191], v[132:135]
	v_mfma_f32_16x16x32_bf16 v[128:131], v[156:159], v[188:191], v[128:131]
	v_mfma_f32_16x16x32_bf16 v[116:119], v[136:139], v[196:199], v[116:119]
	v_mfma_f32_16x16x32_bf16 v[112:115], v[156:159], v[196:199], v[112:115]
	v_mfma_f32_16x16x32_bf16 v[100:103], v[136:139], v[214:217], v[100:103]
	v_mfma_f32_16x16x32_bf16 v[96:99], v[156:159], v[214:217], v[96:99]
	v_mfma_f32_16x16x32_bf16 v[84:87], v[136:139], v[222:225], v[84:87]
	v_mfma_f32_16x16x32_bf16 v[80:83], v[156:159], v[222:225], v[80:83]
	v_mfma_f32_16x16x32_bf16 v[132:135], v[148:151], v[192:195], v[132:135]
	v_mfma_f32_16x16x32_bf16 v[128:131], v[160:163], v[192:195], v[128:131]
	v_mfma_f32_16x16x32_bf16 v[116:119], v[148:151], v[200:203], v[116:119]
	v_mfma_f32_16x16x32_bf16 v[112:115], v[160:163], v[200:203], v[112:115]
	v_mfma_f32_16x16x32_bf16 v[100:103], v[148:151], v[218:221], v[100:103]
	v_mfma_f32_16x16x32_bf16 v[96:99], v[160:163], v[218:221], v[96:99]
	v_mfma_f32_16x16x32_bf16 v[84:87], v[148:151], v[226:229], v[84:87]
	v_mfma_f32_16x16x32_bf16 v[80:83], v[160:163], v[226:229], v[80:83]
	s_setprio 0
	s_setprio 1
	v_mfma_f32_16x16x32_bf16 v[124:127], v[164:167], v[188:191], v[124:127]
	v_mfma_f32_16x16x32_bf16 v[120:123], v[172:175], v[188:191], v[120:123]
	v_mfma_f32_16x16x32_bf16 v[108:111], v[164:167], v[196:199], v[108:111]
	v_mfma_f32_16x16x32_bf16 v[104:107], v[172:175], v[196:199], v[104:107]
	v_mfma_f32_16x16x32_bf16 v[92:95], v[164:167], v[214:217], v[92:95]
	v_mfma_f32_16x16x32_bf16 v[88:91], v[172:175], v[214:217], v[88:91]
	v_mfma_f32_16x16x32_bf16 v[76:79], v[164:167], v[222:225], v[76:79]
	v_mfma_f32_16x16x32_bf16 v[72:75], v[172:175], v[222:225], v[72:75]
	v_mfma_f32_16x16x32_bf16 v[124:127], v[168:171], v[192:195], v[124:127]
	v_mfma_f32_16x16x32_bf16 v[120:123], v[184:187], v[192:195], v[120:123]
	v_mfma_f32_16x16x32_bf16 v[108:111], v[168:171], v[200:203], v[108:111]
	v_mfma_f32_16x16x32_bf16 v[104:107], v[184:187], v[200:203], v[104:107]
	v_mfma_f32_16x16x32_bf16 v[92:95], v[168:171], v[218:221], v[92:95]
	v_mfma_f32_16x16x32_bf16 v[88:91], v[184:187], v[218:221], v[88:91]
	v_mfma_f32_16x16x32_bf16 v[76:79], v[168:171], v[226:229], v[76:79]
	v_mfma_f32_16x16x32_bf16 v[72:75], v[184:187], v[226:229], v[72:75]
	s_setprio 0
	s_barrier
	s_add_u32 s98, s44, s22
	s_addc_u32 s99, s45, s23
	s_add_u32 s100, s46, s22
	s_addc_u32 s101, s47, s23
	s_add_i32 s36, s72, s20
	s_mov_b32 m0, s36
	ds_read_b128 v[188:191], v155 offset:16384
	ds_read_b128 v[192:195], v155 offset:17408
	ds_read_b128 v[196:199], v155 offset:18432
	ds_read_b128 v[200:203], v155 offset:19456
	ds_read_b128 v[214:217], v155 offset:20480
	ds_read_b128 v[218:221], v155 offset:21504
	ds_read_b128 v[222:225], v155 offset:22528
	ds_read_b128 v[226:229], v155 offset:23552
	global_load_lds_dwordx4 v34, s[44:45]
	s_add_i32 m0, s36, 0x2000
	s_add_u32 s36, s44, 0x160000
	s_addc_u32 s37, s45, 0
	s_add_i32 s72, s73, s20
	global_load_lds_dwordx4 v142, s[44:45]
	s_mov_b32 m0, s72
	global_load_lds_dwordx4 v34, s[36:37]
	s_add_i32 m0, s72, 0x2000
	s_nop 0
	global_load_lds_dwordx4 v142, s[36:37]
	s_mov_b32 m0, s25
	s_nop 0
	global_load_lds_dwordx4 v14, s[46:47]
	s_mov_b32 m0, s26
	s_nop 0
	global_load_lds_dwordx4 v140, s[46:47]
	s_waitcnt vmcnt(8)
	s_waitcnt lgkmcnt(0)
	s_barrier
	s_setprio 1
	s_waitcnt lgkmcnt(0)
	v_mfma_f32_16x16x32_bf16 v[68:71], v[136:139], v[188:191], v[68:71]
	v_mfma_f32_16x16x32_bf16 v[64:67], v[156:159], v[188:191], v[64:67]
	v_mfma_f32_16x16x32_bf16 v[52:55], v[136:139], v[196:199], v[52:55]
	v_mfma_f32_16x16x32_bf16 v[48:51], v[156:159], v[196:199], v[48:51]
	v_mfma_f32_16x16x32_bf16 v[36:39], v[136:139], v[214:217], v[36:39]
	v_mfma_f32_16x16x32_bf16 v[30:33], v[156:159], v[214:217], v[30:33]
	v_mfma_f32_16x16x32_bf16 v[18:21], v[136:139], v[222:225], v[18:21]
	v_mfma_f32_16x16x32_bf16 v[10:13], v[156:159], v[222:225], v[10:13]
	v_mfma_f32_16x16x32_bf16 v[68:71], v[148:151], v[192:195], v[68:71]
	v_mfma_f32_16x16x32_bf16 v[64:67], v[160:163], v[192:195], v[64:67]
	v_mfma_f32_16x16x32_bf16 v[52:55], v[148:151], v[200:203], v[52:55]
	v_mfma_f32_16x16x32_bf16 v[48:51], v[160:163], v[200:203], v[48:51]
	v_mfma_f32_16x16x32_bf16 v[36:39], v[148:151], v[218:221], v[36:39]
	v_mfma_f32_16x16x32_bf16 v[30:33], v[160:163], v[218:221], v[30:33]
	v_mfma_f32_16x16x32_bf16 v[18:21], v[148:151], v[226:229], v[18:21]
	v_mfma_f32_16x16x32_bf16 v[10:13], v[160:163], v[226:229], v[10:13]
	s_setprio 0
	s_setprio 1
	v_mfma_f32_16x16x32_bf16 v[60:63], v[164:167], v[188:191], v[60:63]
	v_mfma_f32_16x16x32_bf16 v[56:59], v[172:175], v[188:191], v[56:59]
	v_mfma_f32_16x16x32_bf16 v[44:47], v[164:167], v[196:199], v[44:47]
	v_mfma_f32_16x16x32_bf16 v[40:43], v[172:175], v[196:199], v[40:43]
	v_mfma_f32_16x16x32_bf16 v[26:29], v[164:167], v[214:217], v[26:29]
	v_mfma_f32_16x16x32_bf16 v[22:25], v[172:175], v[214:217], v[22:25]
	v_mfma_f32_16x16x32_bf16 v[6:9], v[164:167], v[222:225], v[6:9]
	v_mfma_f32_16x16x32_bf16 v[2:5], v[172:175], v[222:225], v[2:5]
	v_mfma_f32_16x16x32_bf16 v[60:63], v[168:171], v[192:195], v[60:63]
	v_mfma_f32_16x16x32_bf16 v[56:59], v[184:187], v[192:195], v[56:59]
	v_mfma_f32_16x16x32_bf16 v[44:47], v[168:171], v[200:203], v[44:47]
	v_mfma_f32_16x16x32_bf16 v[40:43], v[184:187], v[200:203], v[40:43]
	v_mfma_f32_16x16x32_bf16 v[26:29], v[168:171], v[218:221], v[26:29]
	v_mfma_f32_16x16x32_bf16 v[22:25], v[184:187], v[218:221], v[22:25]
	v_mfma_f32_16x16x32_bf16 v[6:9], v[168:171], v[226:229], v[6:9]
	v_mfma_f32_16x16x32_bf16 v[2:5], v[184:187], v[226:229], v[2:5]
	s_setprio 0
	s_barrier
	s_add_i32 s72, 0, 0x18000
	s_add_i32 s73, 0, 0x1c000
	v_add_u32_e32 v160, s72, v152
	v_add_u32_e32 v183, s73, v152
	s_add_u32 s36, s46, 0x160000
	s_addc_u32 s37, s47, 0
	s_mov_b32 m0, s27
	global_load_lds_dwordx4 v14, s[36:37]
	s_mov_b32 m0, s31
	s_nop 0
	global_load_lds_dwordx4 v140, s[36:37]
	ds_read_b128 v[136:139], v160
	ds_read_b128 v[148:151], v160 offset:1024
	ds_read_b128 v[156:159], v160 offset:2048
	ds_read_b128 v[160:163], v160 offset:3072
	ds_read_b128 v[164:167], v183
	ds_read_b128 v[168:171], v183 offset:1024
	ds_read_b128 v[172:175], v183 offset:2048
	ds_read_b128 v[184:187], v183 offset:3072
	ds_read_b128 v[188:191], v155 offset:32768
	ds_read_b128 v[192:195], v155 offset:33792
	ds_read_b128 v[196:199], v155 offset:34816
	ds_read_b128 v[200:203], v155 offset:35840
	ds_read_b128 v[214:217], v155 offset:36864
	ds_read_b128 v[218:221], v155 offset:37888
	ds_read_b128 v[222:225], v155 offset:38912
	ds_read_b128 v[226:229], v155 offset:39936
	s_waitcnt vmcnt(8)
	s_waitcnt lgkmcnt(0)
	s_barrier
	s_setprio 1
	s_waitcnt lgkmcnt(0)
	v_mfma_f32_16x16x32_bf16 v[132:135], v[136:139], v[188:191], v[132:135]
	v_mfma_f32_16x16x32_bf16 v[128:131], v[156:159], v[188:191], v[128:131]
	v_mfma_f32_16x16x32_bf16 v[116:119], v[136:139], v[196:199], v[116:119]
	v_mfma_f32_16x16x32_bf16 v[112:115], v[156:159], v[196:199], v[112:115]
	v_mfma_f32_16x16x32_bf16 v[100:103], v[136:139], v[214:217], v[100:103]
	v_mfma_f32_16x16x32_bf16 v[96:99], v[156:159], v[214:217], v[96:99]
	v_mfma_f32_16x16x32_bf16 v[84:87], v[136:139], v[222:225], v[84:87]
	v_mfma_f32_16x16x32_bf16 v[80:83], v[156:159], v[222:225], v[80:83]
	v_mfma_f32_16x16x32_bf16 v[132:135], v[148:151], v[192:195], v[132:135]
	v_mfma_f32_16x16x32_bf16 v[128:131], v[160:163], v[192:195], v[128:131]
	v_mfma_f32_16x16x32_bf16 v[116:119], v[148:151], v[200:203], v[116:119]
	v_mfma_f32_16x16x32_bf16 v[112:115], v[160:163], v[200:203], v[112:115]
	v_mfma_f32_16x16x32_bf16 v[100:103], v[148:151], v[218:221], v[100:103]
	v_mfma_f32_16x16x32_bf16 v[96:99], v[160:163], v[218:221], v[96:99]
	v_mfma_f32_16x16x32_bf16 v[84:87], v[148:151], v[226:229], v[84:87]
	v_mfma_f32_16x16x32_bf16 v[80:83], v[160:163], v[226:229], v[80:83]
	s_setprio 0
	s_setprio 1
	v_mfma_f32_16x16x32_bf16 v[124:127], v[164:167], v[188:191], v[124:127]
	v_mfma_f32_16x16x32_bf16 v[120:123], v[172:175], v[188:191], v[120:123]
	v_mfma_f32_16x16x32_bf16 v[108:111], v[164:167], v[196:199], v[108:111]
	v_mfma_f32_16x16x32_bf16 v[104:107], v[172:175], v[196:199], v[104:107]
	v_mfma_f32_16x16x32_bf16 v[92:95], v[164:167], v[214:217], v[92:95]
	v_mfma_f32_16x16x32_bf16 v[88:91], v[172:175], v[214:217], v[88:91]
	v_mfma_f32_16x16x32_bf16 v[76:79], v[164:167], v[222:225], v[76:79]
	v_mfma_f32_16x16x32_bf16 v[72:75], v[172:175], v[222:225], v[72:75]
	v_mfma_f32_16x16x32_bf16 v[124:127], v[168:171], v[192:195], v[124:127]
	v_mfma_f32_16x16x32_bf16 v[120:123], v[184:187], v[192:195], v[120:123]
	v_mfma_f32_16x16x32_bf16 v[108:111], v[168:171], v[200:203], v[108:111]
	v_mfma_f32_16x16x32_bf16 v[104:107], v[184:187], v[200:203], v[104:107]
	v_mfma_f32_16x16x32_bf16 v[92:95], v[168:171], v[218:221], v[92:95]
	v_mfma_f32_16x16x32_bf16 v[88:91], v[184:187], v[218:221], v[88:91]
	v_mfma_f32_16x16x32_bf16 v[76:79], v[168:171], v[226:229], v[76:79]
	v_mfma_f32_16x16x32_bf16 v[72:75], v[184:187], v[226:229], v[72:75]
	s_setprio 0
	s_barrier
	s_add_i32 s36, s72, s20
	s_mov_b32 m0, s36
	ds_read_b128 v[188:191], v155 offset:49152
	ds_read_b128 v[192:195], v155 offset:50176
	ds_read_b128 v[196:199], v155 offset:51200
	ds_read_b128 v[200:203], v155 offset:52224
	ds_read_b128 v[214:217], v155 offset:53248
	ds_read_b128 v[218:221], v155 offset:54272
	ds_read_b128 v[222:225], v155 offset:55296
	ds_read_b128 v[226:229], v155 offset:56320
	global_load_lds_dwordx4 v34, s[98:99]
	s_add_i32 m0, s36, 0x2000
	s_add_u32 s36, s44, 0x160080
	s_addc_u32 s37, s45, 0
	s_add_i32 s44, s73, s20
	global_load_lds_dwordx4 v142, s[98:99]
	s_mov_b32 m0, s44
	s_nop 0
	global_load_lds_dwordx4 v34, s[36:37]
	s_add_i32 m0, s44, 0x2000
	s_nop 0
	global_load_lds_dwordx4 v142, s[36:37]
	s_mov_b32 m0, s50
	s_nop 0
	global_load_lds_dwordx4 v14, s[100:101]
	s_mov_b32 m0, s51
	s_nop 0
	global_load_lds_dwordx4 v140, s[100:101]
	s_waitcnt vmcnt(8)
	s_waitcnt lgkmcnt(0)
	s_barrier
	s_setprio 1
	s_waitcnt lgkmcnt(0)
	v_mfma_f32_16x16x32_bf16 v[68:71], v[136:139], v[188:191], v[68:71]
	v_mfma_f32_16x16x32_bf16 v[64:67], v[156:159], v[188:191], v[64:67]
	v_mfma_f32_16x16x32_bf16 v[52:55], v[136:139], v[196:199], v[52:55]
	v_mfma_f32_16x16x32_bf16 v[48:51], v[156:159], v[196:199], v[48:51]
	v_mfma_f32_16x16x32_bf16 v[36:39], v[136:139], v[214:217], v[36:39]
	v_mfma_f32_16x16x32_bf16 v[30:33], v[156:159], v[214:217], v[30:33]
	v_mfma_f32_16x16x32_bf16 v[18:21], v[136:139], v[222:225], v[18:21]
	v_mfma_f32_16x16x32_bf16 v[10:13], v[156:159], v[222:225], v[10:13]
	v_mfma_f32_16x16x32_bf16 v[68:71], v[148:151], v[192:195], v[68:71]
	v_mfma_f32_16x16x32_bf16 v[64:67], v[160:163], v[192:195], v[64:67]
	v_mfma_f32_16x16x32_bf16 v[52:55], v[148:151], v[200:203], v[52:55]
	v_mfma_f32_16x16x32_bf16 v[48:51], v[160:163], v[200:203], v[48:51]
	v_mfma_f32_16x16x32_bf16 v[36:39], v[148:151], v[218:221], v[36:39]
	v_mfma_f32_16x16x32_bf16 v[30:33], v[160:163], v[218:221], v[30:33]
	v_mfma_f32_16x16x32_bf16 v[18:21], v[148:151], v[226:229], v[18:21]
	v_mfma_f32_16x16x32_bf16 v[10:13], v[160:163], v[226:229], v[10:13]
	s_setprio 0
	s_setprio 1
	v_mfma_f32_16x16x32_bf16 v[60:63], v[164:167], v[188:191], v[60:63]
	v_mfma_f32_16x16x32_bf16 v[56:59], v[172:175], v[188:191], v[56:59]
	v_mfma_f32_16x16x32_bf16 v[44:47], v[164:167], v[196:199], v[44:47]
	v_mfma_f32_16x16x32_bf16 v[40:43], v[172:175], v[196:199], v[40:43]
	v_mfma_f32_16x16x32_bf16 v[26:29], v[164:167], v[214:217], v[26:29]
	v_mfma_f32_16x16x32_bf16 v[22:25], v[172:175], v[214:217], v[22:25]
	v_mfma_f32_16x16x32_bf16 v[6:9], v[164:167], v[222:225], v[6:9]
	v_mfma_f32_16x16x32_bf16 v[2:5], v[172:175], v[222:225], v[2:5]
	v_mfma_f32_16x16x32_bf16 v[60:63], v[168:171], v[192:195], v[60:63]
	v_mfma_f32_16x16x32_bf16 v[56:59], v[184:187], v[192:195], v[56:59]
	v_mfma_f32_16x16x32_bf16 v[44:47], v[168:171], v[200:203], v[44:47]
	v_mfma_f32_16x16x32_bf16 v[40:43], v[184:187], v[200:203], v[40:43]
	v_mfma_f32_16x16x32_bf16 v[26:29], v[168:171], v[218:221], v[26:29]
	v_mfma_f32_16x16x32_bf16 v[22:25], v[184:187], v[218:221], v[22:25]
	v_mfma_f32_16x16x32_bf16 v[6:9], v[168:171], v[226:229], v[6:9]
	v_mfma_f32_16x16x32_bf16 v[2:5], v[184:187], v[226:229], v[2:5]
	s_setprio 0
	s_barrier
	s_add_u32 s70, s70, 0x100
	s_addc_u32 s71, s71, 0
	s_cmp_ge_i32 vcc_lo, s67
	s_mov_b64 s[36:37], s[42:43]
	s_mov_b32 s44, vcc_lo
	s_cbranch_scc0 .LBB0_1764
	s_mov_b32 s71, 0x200000
	s_and_b64 vcc, exec, s[8:9]
	s_cbranch_vccz .LBB0_1767
